# mixer-in GEMM epilogue: add specialized straight-line log-forget path (same op sequence as generic, 8-wide)
# speedup vs baseline: 1.0160x; 1.0092x over previous
;     __device__ __forceinline__ void operator()(const f32x4 (&acc)[2][2][4][2], const Unit& u, int wr, int wc, int fr, int fq, int ui, PG8_LAS unsigned char* lds) const {
;     ...
;         int act = 0; float sc = 1.f;
;         if (mode == 0) act = (sec == 0 || sec == 3) ? 1 : (sec == 1 ? 2 : 0);
;         else if (mode == 1) sc = (sec == 0) ? qscale : 1.f;
;         else act = 3;
;         const bool ksum = (mode == 1) && (sec == 1);
;         f32x4 csum[2][2] = {{(f32x4){0.f, 0.f, 0.f, 0.f}, (f32x4){0.f, 0.f, 0.f, 0.f}}, {(f32x4){0.f, 0.f, 0.f, 0.f}, (f32x4){0.f, 0.f, 0.f, 0.f}}};
; #pragma unroll
;         for (int ai = 0; ai < 2; ++ai) {
;             float rs4[4];
; #pragma unroll
;             for (int m = 0; m < 4; ++m) {
;                 if ((m & 1) == 0) {
;                     if (use_tab) { rs4[m] = tab[ai * HALF + m * 16] * sc; rs4[m + 1] = tab[ai * HALF + (m + 1) * 16] * sc; }
.LBB0_226:
	s_andn2_b64 vcc, exec, s[40:41]
	s_cbranch_vccnz .Lepi_generic
	s_cmp_eq_u32 s71, 1
	s_cselect_b64 s[38:39], -1, 0
	s_and_b64 s[38:39], s[38:39], s[58:59]
	s_and_b64 vcc, exec, s[38:39]
	s_cbranch_vccnz .Lepi_generic
	s_cmp_eq_u32 s48, 0
	s_cbranch_scc1 .Lepi_id
	s_cmp_eq_u32 s48, 1
	s_cbranch_scc1 .Lepi_silu
	s_cmp_eq_u32 s48, 2
	s_cbranch_scc1 .Lepi_logf
	s_branch .Lepi_generic

; __device__ __forceinline__ unsigned cvt_pk_bf16(float lo, float hi) { unsigned r; asm volatile("v_cvt_pk_bf16_f32 %0, %1, %2" : "=v"(r) : "v"(lo), "v"(hi)); return r; }
; __device__ __forceinline__ float silu_f(float v) { return v * __builtin_amdgcn_rcpf(1.f + __expf(-v)); }
;     __device__ __forceinline__ void operator()(const f32x4 (&acc)[2][2][4][2], const Unit& u, int wr, int wc, int fr, int fq, int ui, PG8_LAS unsigned char* lds) const {
;     ...
;                     f32x4 v[2] = {acc[ai][bj][m][0] * rs, acc[ai][bj][m][1] * rs};
;                     if (ksum) { csum[bj][0] += v[0]; csum[bj][1] += v[1]; }
; #pragma unroll
;                     for (int n = 0; n < 2; ++n) {
;                         f32x4 lbv = (f32x4){0.f, 0.f, 0.f, 0.f};
;                         if (act == 2) lbv = *(const f32x4*)(lb + (col0 - 1024) + bj * HALF + 4 * n);
; #pragma unroll
;                         for (int e = 0; e < 4; ++e) {
;                             float x = v[n][e];
;                             if (act == 1) x = silu_f(x);
;                             else if (act == 2) { const float l = lbv[e]; x = __logf(l + (1.f - l) * __builtin_amdgcn_rcpf(1.f + __expf(-x))); }
;                             else if (act == 3) { x = fmaxf(x, 0.f); x = x * x; }
;                             v[n][e] = x;
;                         }
;                     }
;                     u32x4 w; w.x = cvt_pk_bf16(v[0][0], v[0][1]); w.y = cvt_pk_bf16(v[0][2], v[0][3]); w.z = cvt_pk_bf16(v[1][0], v[1][1]); w.w = cvt_pk_bf16(v[1][2], v[1][3]);
;                     *(u32x4*)(rowp + bj * HALF) = w;
.Lepi_logf:
	v_lshl_add_u32 v150, s78, 8, v164
	s_lshl_b32 s1, s1, 10
	v_add_u32_e32 v170, s1, v166
	ds_read_b32 v128, v170
	ds_read_b32 v130, v170 offset:64
	ds_read_b32 v144, v170 offset:128
	ds_read_b32 v146, v170 offset:192
	ds_read_b32 v148, v170 offset:512
	ds_read_b32 v156, v170 offset:576
	ds_read_b32 v158, v170 offset:640
	ds_read_b32 v160, v170 offset:704
	s_lshl_b32 s73, s0, 8
	v_or_b32_e32 v172, s73, v167
	v_mov_b32_e32 v173, 0
	v_mad_u64_u32 v[162:163], s[38:39], v150, s96, 0
	s_lshl_b32 s46, s96, 5
	s_mov_b32 s47, 0
	s_lshl_b32 s52, s96, 8
	s_mov_b32 s53, 0
	v_lshl_add_u64 v[162:163], v[162:163], 1, s[14:15]
	v_lshl_add_u64 v[162:163], v[172:173], 1, v[162:163]
	v_lshl_add_u64 v[178:179], v[162:163], 0, s[52:53]
	s_waitcnt lgkmcnt(0)
	v_mul_f32_e32 v128, v169, v128
	v_mul_f32_e32 v130, v169, v130
	v_mul_f32_e32 v144, v169, v144
	v_mul_f32_e32 v146, v169, v146
	v_mul_f32_e32 v148, v169, v148
	v_mul_f32_e32 v156, v169, v156
	v_mul_f32_e32 v158, v169, v158
	v_mul_f32_e32 v160, v169, v160
	v_lshl_add_u64 v[170:171], v[172:173], 2, s[64:65]
	global_load_dwordx4 v[152:155], v[170:171], off offset:-4096
	global_load_dwordx4 v[180:183], v[170:171], off offset:-4080
	global_load_dwordx4 v[218:221], v[170:171], off offset:-3584
	global_load_dwordx4 v[222:225], v[170:171], off offset:-3568
	s_waitcnt vmcnt(0)
	v_pk_mul_f32 v[124:125], v[124:125], v[128:129] op_sel_hi:[1,0]
	v_pk_mul_f32 v[126:127], v[126:127], v[128:129] op_sel_hi:[1,0]
	v_pk_mul_f32 v[120:121], v[120:121], v[128:129] op_sel_hi:[1,0]
	v_pk_mul_f32 v[122:123], v[122:123], v[128:129] op_sel_hi:[1,0]
	v_mul_f32_e32 v184, 0xbfb8aa3b, v124
	v_mul_f32_e32 v185, 0xbfb8aa3b, v125
	v_mul_f32_e32 v186, 0xbfb8aa3b, v126
	v_mul_f32_e32 v187, 0xbfb8aa3b, v127
	v_mul_f32_e32 v188, 0xbfb8aa3b, v120
	v_mul_f32_e32 v189, 0xbfb8aa3b, v121
	v_mul_f32_e32 v190, 0xbfb8aa3b, v122
	v_mul_f32_e32 v191, 0xbfb8aa3b, v123
	v_exp_f32_e32 v184, v184
	v_exp_f32_e32 v185, v185
	v_exp_f32_e32 v186, v186
	v_exp_f32_e32 v187, v187
	v_exp_f32_e32 v188, v188
	v_exp_f32_e32 v189, v189
	v_exp_f32_e32 v190, v190
	v_exp_f32_e32 v191, v191
	v_sub_f32_e32 v192, 1.0, v152
	v_sub_f32_e32 v193, 1.0, v153
	v_sub_f32_e32 v194, 1.0, v154
	v_sub_f32_e32 v195, 1.0, v155
	v_sub_f32_e32 v196, 1.0, v180
	v_sub_f32_e32 v197, 1.0, v181
	v_sub_f32_e32 v198, 1.0, v182
	v_sub_f32_e32 v199, 1.0, v183
	v_add_f32_e32 v184, 1.0, v184
	v_add_f32_e32 v185, 1.0, v185
	v_add_f32_e32 v186, 1.0, v186
	v_add_f32_e32 v187, 1.0, v187
	v_add_f32_e32 v188, 1.0, v188
	v_add_f32_e32 v189, 1.0, v189
	v_add_f32_e32 v190, 1.0, v190
	v_add_f32_e32 v191, 1.0, v191
	v_rcp_f32_e32 v184, v184
	v_rcp_f32_e32 v185, v185
	v_rcp_f32_e32 v186, v186
	v_rcp_f32_e32 v187, v187
	v_rcp_f32_e32 v188, v188
	v_rcp_f32_e32 v189, v189
	v_rcp_f32_e32 v190, v190
	v_rcp_f32_e32 v191, v191
	v_fma_f32 v200, v184, v192, v152
	v_fma_f32 v201, v185, v193, v153
	v_fma_f32 v202, v186, v194, v154
	v_fma_f32 v203, v187, v195, v155
	v_fma_f32 v204, v188, v196, v180
	v_fma_f32 v205, v189, v197, v181
	v_fma_f32 v206, v190, v198, v182
	v_fma_f32 v207, v191, v199, v183
	v_cmp_gt_f32_e64 vcc, s35, v200
	v_cmp_gt_f32_e64 s[38:39], s35, v201
	v_cmp_gt_f32_e64 s[48:49], s35, v202
	v_cmp_gt_f32_e64 s[50:51], s35, v203
	v_cndmask_b32_e64 v184, 0, 32, vcc
	v_cndmask_b32_e64 v185, 0, 32, s[38:39]
	v_cndmask_b32_e64 v186, 0, 32, s[48:49]
	v_cndmask_b32_e64 v187, 0, 32, s[50:51]
	v_cndmask_b32_e64 v192, 0, v214, vcc
	v_cndmask_b32_e64 v193, 0, v214, s[38:39]
	v_cndmask_b32_e64 v194, 0, v214, s[48:49]
	v_cndmask_b32_e64 v195, 0, v214, s[50:51]
	v_cmp_gt_f32_e64 vcc, s35, v204
	v_cmp_gt_f32_e64 s[38:39], s35, v205
	v_cmp_gt_f32_e64 s[48:49], s35, v206
	v_cmp_gt_f32_e64 s[50:51], s35, v207
	v_cndmask_b32_e64 v188, 0, 32, vcc
	v_cndmask_b32_e64 v189, 0, 32, s[38:39]
	v_cndmask_b32_e64 v190, 0, 32, s[48:49]
	v_cndmask_b32_e64 v191, 0, 32, s[50:51]
	v_cndmask_b32_e64 v196, 0, v214, vcc
	v_cndmask_b32_e64 v197, 0, v214, s[38:39]
	v_cndmask_b32_e64 v198, 0, v214, s[48:49]
	v_cndmask_b32_e64 v199, 0, v214, s[50:51]
	v_ldexp_f32 v184, v200, v184
	v_ldexp_f32 v185, v201, v185
	v_ldexp_f32 v186, v202, v186
	v_ldexp_f32 v187, v203, v187
	v_ldexp_f32 v188, v204, v188
	v_ldexp_f32 v189, v205, v189
	v_ldexp_f32 v190, v206, v190
	v_ldexp_f32 v191, v207, v191
	v_log_f32_e32 v184, v184
	v_log_f32_e32 v185, v185
	v_log_f32_e32 v186, v186
	v_log_f32_e32 v187, v187
	v_log_f32_e32 v188, v188
	v_log_f32_e32 v189, v189
	v_log_f32_e32 v190, v190
	v_log_f32_e32 v191, v191
	v_mul_f32_e32 v200, 0x3f317217, v184
	v_mul_f32_e32 v201, 0x3f317217, v185
	v_mul_f32_e32 v202, 0x3f317217, v186
	v_mul_f32_e32 v203, 0x3f317217, v187
	v_mul_f32_e32 v204, 0x3f317217, v188
	v_mul_f32_e32 v205, 0x3f317217, v189
	v_mul_f32_e32 v206, 0x3f317217, v190
	v_mul_f32_e32 v207, 0x3f317217, v191
	v_fma_f32 v200, v184, s13, -v200
	v_fma_f32 v201, v185, s13, -v201
	v_fma_f32 v202, v186, s13, -v202
	v_fma_f32 v203, v187, s13, -v203
	v_fma_f32 v204, v188, s13, -v204
	v_fma_f32 v205, v189, s13, -v205
	v_fma_f32 v206, v190, s13, -v206
	v_fma_f32 v207, v191, s13, -v207
	v_fmac_f32_e32 v200, 0x3377d1cf, v184
	v_fmac_f32_e32 v201, 0x3377d1cf, v185
	v_fmac_f32_e32 v202, 0x3377d1cf, v186
	v_fmac_f32_e32 v203, 0x3377d1cf, v187
	v_fmac_f32_e32 v204, 0x3377d1cf, v188
	v_fmac_f32_e32 v205, 0x3377d1cf, v189
	v_fmac_f32_e32 v206, 0x3377d1cf, v190
	v_fmac_f32_e32 v207, 0x3377d1cf, v191
	v_fmac_f32_e32 v200, 0x3f317217, v184
	v_fmac_f32_e32 v201, 0x3f317217, v185
	v_fmac_f32_e32 v202, 0x3f317217, v186
	v_fmac_f32_e32 v203, 0x3f317217, v187
	v_fmac_f32_e32 v204, 0x3f317217, v188
	v_fmac_f32_e32 v205, 0x3f317217, v189
	v_fmac_f32_e32 v206, 0x3f317217, v190
; __device__ __forceinline__ unsigned cvt_pk_bf16(float lo, float hi) { unsigned r; asm volatile("v_cvt_pk_bf16_f32 %0, %1, %2" : "=v"(r) : "v"(lo), "v"(hi)); return r; }
; __device__ __forceinline__ float silu_f(float v) { return v * __builtin_amdgcn_rcpf(1.f + __expf(-v)); }
;     __device__ __forceinline__ void operator()(const f32x4 (&acc)[2][2][4][2], const Unit& u, int wr, int wc, int fr, int fq, int ui, PG8_LAS unsigned char* lds) const {
;     ...
;                     f32x4 v[2] = {acc[ai][bj][m][0] * rs, acc[ai][bj][m][1] * rs};
;                     if (ksum) { csum[bj][0] += v[0]; csum[bj][1] += v[1]; }
; #pragma unroll
;                     for (int n = 0; n < 2; ++n) {
;                         f32x4 lbv = (f32x4){0.f, 0.f, 0.f, 0.f};
;                         if (act == 2) lbv = *(const f32x4*)(lb + (col0 - 1024) + bj * HALF + 4 * n);
; #pragma unroll
;                         for (int e = 0; e < 4; ++e) {
;                             float x = v[n][e];
;                             if (act == 1) x = silu_f(x);
;                             else if (act == 2) { const float l = lbv[e]; x = __logf(l + (1.f - l) * __builtin_amdgcn_rcpf(1.f + __expf(-x))); }
;                             else if (act == 3) { x = fmaxf(x, 0.f); x = x * x; }
;                             v[n][e] = x;
;                         }
;                     }
;                     u32x4 w; w.x = cvt_pk_bf16(v[0][0], v[0][1]); w.y = cvt_pk_bf16(v[0][2], v[0][3]); w.z = cvt_pk_bf16(v[1][0], v[1][1]); w.w = cvt_pk_bf16(v[1][2], v[1][3]);
;                     *(u32x4*)(rowp + bj * HALF) = w;
	v_fmac_f32_e32 v207, 0x3f317217, v191
	v_cmp_lt_f32_e64 vcc, |v184|, s36
	v_cmp_lt_f32_e64 s[38:39], |v185|, s36
	v_cmp_lt_f32_e64 s[48:49], |v186|, s36
	v_cmp_lt_f32_e64 s[50:51], |v187|, s36
	v_cndmask_b32_e64 v184, v184, v200, vcc
	v_cndmask_b32_e64 v185, v185, v201, s[38:39]
	v_cndmask_b32_e64 v186, v186, v202, s[48:49]
	v_cndmask_b32_e64 v187, v187, v203, s[50:51]
	v_cmp_lt_f32_e64 vcc, |v188|, s36
	v_cmp_lt_f32_e64 s[38:39], |v189|, s36
	v_cmp_lt_f32_e64 s[48:49], |v190|, s36
	v_cmp_lt_f32_e64 s[50:51], |v191|, s36
	v_cndmask_b32_e64 v188, v188, v204, vcc
	v_cndmask_b32_e64 v189, v189, v205, s[38:39]
	v_cndmask_b32_e64 v190, v190, v206, s[48:49]
	v_cndmask_b32_e64 v191, v191, v207, s[50:51]
	v_sub_f32_e32 v124, v184, v192
	v_sub_f32_e32 v125, v185, v193
	v_sub_f32_e32 v126, v186, v194
	v_sub_f32_e32 v127, v187, v195
	v_sub_f32_e32 v120, v188, v196
	v_sub_f32_e32 v121, v189, v197
	v_sub_f32_e32 v122, v190, v198
	v_sub_f32_e32 v123, v191, v199
	v_cvt_pk_bf16_f32 v124, v124, v125
	v_cvt_pk_bf16_f32 v125, v126, v127
	v_cvt_pk_bf16_f32 v126, v120, v121
	v_cvt_pk_bf16_f32 v127, v122, v123
	global_store_dwordx4 v[162:163], v[124:127], off
	v_pk_mul_f32 v[116:117], v[116:117], v[128:129] op_sel_hi:[1,0]
	v_pk_mul_f32 v[118:119], v[118:119], v[128:129] op_sel_hi:[1,0]
	v_pk_mul_f32 v[112:113], v[112:113], v[128:129] op_sel_hi:[1,0]
	v_pk_mul_f32 v[114:115], v[114:115], v[128:129] op_sel_hi:[1,0]
	v_mul_f32_e32 v184, 0xbfb8aa3b, v116
	v_mul_f32_e32 v185, 0xbfb8aa3b, v117
	v_mul_f32_e32 v186, 0xbfb8aa3b, v118
	v_mul_f32_e32 v187, 0xbfb8aa3b, v119
	v_mul_f32_e32 v188, 0xbfb8aa3b, v112
	v_mul_f32_e32 v189, 0xbfb8aa3b, v113
	v_mul_f32_e32 v190, 0xbfb8aa3b, v114
	v_mul_f32_e32 v191, 0xbfb8aa3b, v115
	v_exp_f32_e32 v184, v184
	v_exp_f32_e32 v185, v185
	v_exp_f32_e32 v186, v186
	v_exp_f32_e32 v187, v187
	v_exp_f32_e32 v188, v188
	v_exp_f32_e32 v189, v189
	v_exp_f32_e32 v190, v190
	v_exp_f32_e32 v191, v191
	v_sub_f32_e32 v192, 1.0, v218
	v_sub_f32_e32 v193, 1.0, v219
	v_sub_f32_e32 v194, 1.0, v220
	v_sub_f32_e32 v195, 1.0, v221
	v_sub_f32_e32 v196, 1.0, v222
	v_sub_f32_e32 v197, 1.0, v223
	v_sub_f32_e32 v198, 1.0, v224
	v_sub_f32_e32 v199, 1.0, v225
	v_add_f32_e32 v184, 1.0, v184
	v_add_f32_e32 v185, 1.0, v185
	v_add_f32_e32 v186, 1.0, v186
	v_add_f32_e32 v187, 1.0, v187
	v_add_f32_e32 v188, 1.0, v188
	v_add_f32_e32 v189, 1.0, v189
	v_add_f32_e32 v190, 1.0, v190
	v_add_f32_e32 v191, 1.0, v191
	v_rcp_f32_e32 v184, v184
	v_rcp_f32_e32 v185, v185
	v_rcp_f32_e32 v186, v186
	v_rcp_f32_e32 v187, v187
	v_rcp_f32_e32 v188, v188
	v_rcp_f32_e32 v189, v189
	v_rcp_f32_e32 v190, v190
	v_rcp_f32_e32 v191, v191
	v_fma_f32 v200, v184, v192, v218
	v_fma_f32 v201, v185, v193, v219
	v_fma_f32 v202, v186, v194, v220
	v_fma_f32 v203, v187, v195, v221
	v_fma_f32 v204, v188, v196, v222
	v_fma_f32 v205, v189, v197, v223
	v_fma_f32 v206, v190, v198, v224
	v_fma_f32 v207, v191, v199, v225
	v_cmp_gt_f32_e64 vcc, s35, v200
	v_cmp_gt_f32_e64 s[38:39], s35, v201
	v_cmp_gt_f32_e64 s[48:49], s35, v202
	v_cmp_gt_f32_e64 s[50:51], s35, v203
	v_cndmask_b32_e64 v184, 0, 32, vcc
	v_cndmask_b32_e64 v185, 0, 32, s[38:39]
	v_cndmask_b32_e64 v186, 0, 32, s[48:49]
	v_cndmask_b32_e64 v187, 0, 32, s[50:51]
	v_cndmask_b32_e64 v192, 0, v214, vcc
	v_cndmask_b32_e64 v193, 0, v214, s[38:39]
	v_cndmask_b32_e64 v194, 0, v214, s[48:49]
	v_cndmask_b32_e64 v195, 0, v214, s[50:51]
	v_cmp_gt_f32_e64 vcc, s35, v204
	v_cmp_gt_f32_e64 s[38:39], s35, v205
	v_cmp_gt_f32_e64 s[48:49], s35, v206
	v_cmp_gt_f32_e64 s[50:51], s35, v207
	v_cndmask_b32_e64 v188, 0, 32, vcc
	v_cndmask_b32_e64 v189, 0, 32, s[38:39]
	v_cndmask_b32_e64 v190, 0, 32, s[48:49]
	v_cndmask_b32_e64 v191, 0, 32, s[50:51]
	v_cndmask_b32_e64 v196, 0, v214, vcc
	v_cndmask_b32_e64 v197, 0, v214, s[38:39]
	v_cndmask_b32_e64 v198, 0, v214, s[48:49]
	v_cndmask_b32_e64 v199, 0, v214, s[50:51]
	v_ldexp_f32 v184, v200, v184
	v_ldexp_f32 v185, v201, v185
	v_ldexp_f32 v186, v202, v186
	v_ldexp_f32 v187, v203, v187
	v_ldexp_f32 v188, v204, v188
	v_ldexp_f32 v189, v205, v189
	v_ldexp_f32 v190, v206, v190
	v_ldexp_f32 v191, v207, v191
	v_log_f32_e32 v184, v184
	v_log_f32_e32 v185, v185
	v_log_f32_e32 v186, v186
	v_log_f32_e32 v187, v187
	v_log_f32_e32 v188, v188
	v_log_f32_e32 v189, v189
	v_log_f32_e32 v190, v190
	v_log_f32_e32 v191, v191
	v_mul_f32_e32 v200, 0x3f317217, v184
	v_mul_f32_e32 v201, 0x3f317217, v185
	v_mul_f32_e32 v202, 0x3f317217, v186
	v_mul_f32_e32 v203, 0x3f317217, v187
	v_mul_f32_e32 v204, 0x3f317217, v188
	v_mul_f32_e32 v205, 0x3f317217, v189
	v_mul_f32_e32 v206, 0x3f317217, v190
	v_mul_f32_e32 v207, 0x3f317217, v191
	v_fma_f32 v200, v184, s13, -v200
	v_fma_f32 v201, v185, s13, -v201
	v_fma_f32 v202, v186, s13, -v202
	v_fma_f32 v203, v187, s13, -v203
	v_fma_f32 v204, v188, s13, -v204
	v_fma_f32 v205, v189, s13, -v205
	v_fma_f32 v206, v190, s13, -v206
	v_fma_f32 v207, v191, s13, -v207
	v_fmac_f32_e32 v200, 0x3377d1cf, v184
	v_fmac_f32_e32 v201, 0x3377d1cf, v185
	v_fmac_f32_e32 v202, 0x3377d1cf, v186
	v_fmac_f32_e32 v203, 0x3377d1cf, v187
	v_fmac_f32_e32 v204, 0x3377d1cf, v188
	v_fmac_f32_e32 v205, 0x3377d1cf, v189
	v_fmac_f32_e32 v206, 0x3377d1cf, v190
	v_fmac_f32_e32 v207, 0x3377d1cf, v191
	v_fmac_f32_e32 v200, 0x3f317217, v184
	v_fmac_f32_e32 v201, 0x3f317217, v185
	v_fmac_f32_e32 v202, 0x3f317217, v186
	v_fmac_f32_e32 v203, 0x3f317217, v187
	v_fmac_f32_e32 v204, 0x3f317217, v188
	v_fmac_f32_e32 v205, 0x3f317217, v189
	v_fmac_f32_e32 v206, 0x3f317217, v190
	v_fmac_f32_e32 v207, 0x3f317217, v191
	v_cmp_lt_f32_e64 vcc, |v184|, s36
	v_cmp_lt_f32_e64 s[38:39], |v185|, s36
	v_cmp_lt_f32_e64 s[48:49], |v186|, s36
	v_cmp_lt_f32_e64 s[50:51], |v187|, s36
; __device__ __forceinline__ unsigned cvt_pk_bf16(float lo, float hi) { unsigned r; asm volatile("v_cvt_pk_bf16_f32 %0, %1, %2" : "=v"(r) : "v"(lo), "v"(hi)); return r; }
; __device__ __forceinline__ float silu_f(float v) { return v * __builtin_amdgcn_rcpf(1.f + __expf(-v)); }
;     __device__ __forceinline__ void operator()(const f32x4 (&acc)[2][2][4][2], const Unit& u, int wr, int wc, int fr, int fq, int ui, PG8_LAS unsigned char* lds) const {
;     ...
;                     f32x4 v[2] = {acc[ai][bj][m][0] * rs, acc[ai][bj][m][1] * rs};
;                     if (ksum) { csum[bj][0] += v[0]; csum[bj][1] += v[1]; }
; #pragma unroll
;                     for (int n = 0; n < 2; ++n) {
;                         f32x4 lbv = (f32x4){0.f, 0.f, 0.f, 0.f};
;                         if (act == 2) lbv = *(const f32x4*)(lb + (col0 - 1024) + bj * HALF + 4 * n);
; #pragma unroll
;                         for (int e = 0; e < 4; ++e) {
;                             float x = v[n][e];
;                             if (act == 1) x = silu_f(x);
;                             else if (act == 2) { const float l = lbv[e]; x = __logf(l + (1.f - l) * __builtin_amdgcn_rcpf(1.f + __expf(-x))); }
;                             else if (act == 3) { x = fmaxf(x, 0.f); x = x * x; }
;                             v[n][e] = x;
;                         }
;                     }
;                     u32x4 w; w.x = cvt_pk_bf16(v[0][0], v[0][1]); w.y = cvt_pk_bf16(v[0][2], v[0][3]); w.z = cvt_pk_bf16(v[1][0], v[1][1]); w.w = cvt_pk_bf16(v[1][2], v[1][3]);
;                     *(u32x4*)(rowp + bj * HALF) = w;
	v_cndmask_b32_e64 v184, v184, v200, vcc
	v_cndmask_b32_e64 v185, v185, v201, s[38:39]
	v_cndmask_b32_e64 v186, v186, v202, s[48:49]
	v_cndmask_b32_e64 v187, v187, v203, s[50:51]
	v_cmp_lt_f32_e64 vcc, |v188|, s36
	v_cmp_lt_f32_e64 s[38:39], |v189|, s36
	v_cmp_lt_f32_e64 s[48:49], |v190|, s36
	v_cmp_lt_f32_e64 s[50:51], |v191|, s36
	v_cndmask_b32_e64 v188, v188, v204, vcc
	v_cndmask_b32_e64 v189, v189, v205, s[38:39]
	v_cndmask_b32_e64 v190, v190, v206, s[48:49]
	v_cndmask_b32_e64 v191, v191, v207, s[50:51]
	v_sub_f32_e32 v116, v184, v192
	v_sub_f32_e32 v117, v185, v193
	v_sub_f32_e32 v118, v186, v194
	v_sub_f32_e32 v119, v187, v195
	v_sub_f32_e32 v112, v188, v196
	v_sub_f32_e32 v113, v189, v197
	v_sub_f32_e32 v114, v190, v198
	v_sub_f32_e32 v115, v191, v199
	v_cvt_pk_bf16_f32 v116, v116, v117
	v_cvt_pk_bf16_f32 v117, v118, v119
	v_cvt_pk_bf16_f32 v118, v112, v113
	v_cvt_pk_bf16_f32 v119, v114, v115
	global_store_dwordx4 v[162:163], v[116:119], off offset:256
	v_lshl_add_u64 v[176:177], v[162:163], 0, s[46:47]
	v_pk_mul_f32 v[108:109], v[108:109], v[130:131] op_sel_hi:[1,0]
	v_pk_mul_f32 v[110:111], v[110:111], v[130:131] op_sel_hi:[1,0]
	v_pk_mul_f32 v[104:105], v[104:105], v[130:131] op_sel_hi:[1,0]
	v_pk_mul_f32 v[106:107], v[106:107], v[130:131] op_sel_hi:[1,0]
	v_mul_f32_e32 v184, 0xbfb8aa3b, v108
	v_mul_f32_e32 v185, 0xbfb8aa3b, v109
	v_mul_f32_e32 v186, 0xbfb8aa3b, v110
	v_mul_f32_e32 v187, 0xbfb8aa3b, v111
	v_mul_f32_e32 v188, 0xbfb8aa3b, v104
	v_mul_f32_e32 v189, 0xbfb8aa3b, v105
	v_mul_f32_e32 v190, 0xbfb8aa3b, v106
	v_mul_f32_e32 v191, 0xbfb8aa3b, v107
	v_exp_f32_e32 v184, v184
	v_exp_f32_e32 v185, v185
	v_exp_f32_e32 v186, v186
	v_exp_f32_e32 v187, v187
	v_exp_f32_e32 v188, v188
	v_exp_f32_e32 v189, v189
	v_exp_f32_e32 v190, v190
	v_exp_f32_e32 v191, v191
	v_sub_f32_e32 v192, 1.0, v152
	v_sub_f32_e32 v193, 1.0, v153
	v_sub_f32_e32 v194, 1.0, v154
	v_sub_f32_e32 v195, 1.0, v155
	v_sub_f32_e32 v196, 1.0, v180
	v_sub_f32_e32 v197, 1.0, v181
	v_sub_f32_e32 v198, 1.0, v182
	v_sub_f32_e32 v199, 1.0, v183
	v_add_f32_e32 v184, 1.0, v184
	v_add_f32_e32 v185, 1.0, v185
	v_add_f32_e32 v186, 1.0, v186
	v_add_f32_e32 v187, 1.0, v187
	v_add_f32_e32 v188, 1.0, v188
	v_add_f32_e32 v189, 1.0, v189
	v_add_f32_e32 v190, 1.0, v190
	v_add_f32_e32 v191, 1.0, v191
	v_rcp_f32_e32 v184, v184
	v_rcp_f32_e32 v185, v185
	v_rcp_f32_e32 v186, v186
	v_rcp_f32_e32 v187, v187
	v_rcp_f32_e32 v188, v188
	v_rcp_f32_e32 v189, v189
	v_rcp_f32_e32 v190, v190
	v_rcp_f32_e32 v191, v191
	v_fma_f32 v200, v184, v192, v152
	v_fma_f32 v201, v185, v193, v153
	v_fma_f32 v202, v186, v194, v154
	v_fma_f32 v203, v187, v195, v155
	v_fma_f32 v204, v188, v196, v180
	v_fma_f32 v205, v189, v197, v181
	v_fma_f32 v206, v190, v198, v182
	v_fma_f32 v207, v191, v199, v183
	v_cmp_gt_f32_e64 vcc, s35, v200
	v_cmp_gt_f32_e64 s[38:39], s35, v201
	v_cmp_gt_f32_e64 s[48:49], s35, v202
	v_cmp_gt_f32_e64 s[50:51], s35, v203
	v_cndmask_b32_e64 v184, 0, 32, vcc
	v_cndmask_b32_e64 v185, 0, 32, s[38:39]
	v_cndmask_b32_e64 v186, 0, 32, s[48:49]
	v_cndmask_b32_e64 v187, 0, 32, s[50:51]
	v_cndmask_b32_e64 v192, 0, v214, vcc
	v_cndmask_b32_e64 v193, 0, v214, s[38:39]
	v_cndmask_b32_e64 v194, 0, v214, s[48:49]
	v_cndmask_b32_e64 v195, 0, v214, s[50:51]
	v_cmp_gt_f32_e64 vcc, s35, v204
	v_cmp_gt_f32_e64 s[38:39], s35, v205
	v_cmp_gt_f32_e64 s[48:49], s35, v206
	v_cmp_gt_f32_e64 s[50:51], s35, v207
	v_cndmask_b32_e64 v188, 0, 32, vcc
	v_cndmask_b32_e64 v189, 0, 32, s[38:39]
	v_cndmask_b32_e64 v190, 0, 32, s[48:49]
	v_cndmask_b32_e64 v191, 0, 32, s[50:51]
	v_cndmask_b32_e64 v196, 0, v214, vcc
	v_cndmask_b32_e64 v197, 0, v214, s[38:39]
	v_cndmask_b32_e64 v198, 0, v214, s[48:49]
	v_cndmask_b32_e64 v199, 0, v214, s[50:51]
	v_ldexp_f32 v184, v200, v184
	v_ldexp_f32 v185, v201, v185
	v_ldexp_f32 v186, v202, v186
	v_ldexp_f32 v187, v203, v187
	v_ldexp_f32 v188, v204, v188
	v_ldexp_f32 v189, v205, v189
	v_ldexp_f32 v190, v206, v190
	v_ldexp_f32 v191, v207, v191
	v_log_f32_e32 v184, v184
	v_log_f32_e32 v185, v185
	v_log_f32_e32 v186, v186
	v_log_f32_e32 v187, v187
	v_log_f32_e32 v188, v188
	v_log_f32_e32 v189, v189
	v_log_f32_e32 v190, v190
	v_log_f32_e32 v191, v191
	v_mul_f32_e32 v200, 0x3f317217, v184
	v_mul_f32_e32 v201, 0x3f317217, v185
	v_mul_f32_e32 v202, 0x3f317217, v186
	v_mul_f32_e32 v203, 0x3f317217, v187
	v_mul_f32_e32 v204, 0x3f317217, v188
	v_mul_f32_e32 v205, 0x3f317217, v189
	v_mul_f32_e32 v206, 0x3f317217, v190
	v_mul_f32_e32 v207, 0x3f317217, v191
	v_fma_f32 v200, v184, s13, -v200
	v_fma_f32 v201, v185, s13, -v201
	v_fma_f32 v202, v186, s13, -v202
	v_fma_f32 v203, v187, s13, -v203
	v_fma_f32 v204, v188, s13, -v204
	v_fma_f32 v205, v189, s13, -v205
	v_fma_f32 v206, v190, s13, -v206
	v_fma_f32 v207, v191, s13, -v207
	v_fmac_f32_e32 v200, 0x3377d1cf, v184
	v_fmac_f32_e32 v201, 0x3377d1cf, v185
	v_fmac_f32_e32 v202, 0x3377d1cf, v186
	v_fmac_f32_e32 v203, 0x3377d1cf, v187
	v_fmac_f32_e32 v204, 0x3377d1cf, v188
	v_fmac_f32_e32 v205, 0x3377d1cf, v189
	v_fmac_f32_e32 v206, 0x3377d1cf, v190
	v_fmac_f32_e32 v207, 0x3377d1cf, v191
	v_fmac_f32_e32 v200, 0x3f317217, v184
	v_fmac_f32_e32 v201, 0x3f317217, v185
	v_fmac_f32_e32 v202, 0x3f317217, v186
	v_fmac_f32_e32 v203, 0x3f317217, v187
	v_fmac_f32_e32 v204, 0x3f317217, v188
	v_fmac_f32_e32 v205, 0x3f317217, v189
	v_fmac_f32_e32 v206, 0x3f317217, v190
	v_fmac_f32_e32 v207, 0x3f317217, v191
	v_cmp_lt_f32_e64 vcc, |v184|, s36
	v_cmp_lt_f32_e64 s[38:39], |v185|, s36
	v_cmp_lt_f32_e64 s[48:49], |v186|, s36
	v_cmp_lt_f32_e64 s[50:51], |v187|, s36
	v_cndmask_b32_e64 v184, v184, v200, vcc
	v_cndmask_b32_e64 v185, v185, v201, s[38:39]
	v_cndmask_b32_e64 v186, v186, v202, s[48:49]
; __device__ __forceinline__ unsigned cvt_pk_bf16(float lo, float hi) { unsigned r; asm volatile("v_cvt_pk_bf16_f32 %0, %1, %2" : "=v"(r) : "v"(lo), "v"(hi)); return r; }
; __device__ __forceinline__ float silu_f(float v) { return v * __builtin_amdgcn_rcpf(1.f + __expf(-v)); }
;     __device__ __forceinline__ void operator()(const f32x4 (&acc)[2][2][4][2], const Unit& u, int wr, int wc, int fr, int fq, int ui, PG8_LAS unsigned char* lds) const {
;     ...
;                     f32x4 v[2] = {acc[ai][bj][m][0] * rs, acc[ai][bj][m][1] * rs};
;                     if (ksum) { csum[bj][0] += v[0]; csum[bj][1] += v[1]; }
; #pragma unroll
;                     for (int n = 0; n < 2; ++n) {
;                         f32x4 lbv = (f32x4){0.f, 0.f, 0.f, 0.f};
;                         if (act == 2) lbv = *(const f32x4*)(lb + (col0 - 1024) + bj * HALF + 4 * n);
; #pragma unroll
;                         for (int e = 0; e < 4; ++e) {
;                             float x = v[n][e];
;                             if (act == 1) x = silu_f(x);
;                             else if (act == 2) { const float l = lbv[e]; x = __logf(l + (1.f - l) * __builtin_amdgcn_rcpf(1.f + __expf(-x))); }
;                             else if (act == 3) { x = fmaxf(x, 0.f); x = x * x; }
;                             v[n][e] = x;
;                         }
;                     }
;                     u32x4 w; w.x = cvt_pk_bf16(v[0][0], v[0][1]); w.y = cvt_pk_bf16(v[0][2], v[0][3]); w.z = cvt_pk_bf16(v[1][0], v[1][1]); w.w = cvt_pk_bf16(v[1][2], v[1][3]);
;                     *(u32x4*)(rowp + bj * HALF) = w;
	v_cndmask_b32_e64 v187, v187, v203, s[50:51]
	v_cmp_lt_f32_e64 vcc, |v188|, s36
	v_cmp_lt_f32_e64 s[38:39], |v189|, s36
	v_cmp_lt_f32_e64 s[48:49], |v190|, s36
	v_cmp_lt_f32_e64 s[50:51], |v191|, s36
	v_cndmask_b32_e64 v188, v188, v204, vcc
	v_cndmask_b32_e64 v189, v189, v205, s[38:39]
	v_cndmask_b32_e64 v190, v190, v206, s[48:49]
	v_cndmask_b32_e64 v191, v191, v207, s[50:51]
	v_sub_f32_e32 v108, v184, v192
	v_sub_f32_e32 v109, v185, v193
	v_sub_f32_e32 v110, v186, v194
	v_sub_f32_e32 v111, v187, v195
	v_sub_f32_e32 v104, v188, v196
	v_sub_f32_e32 v105, v189, v197
	v_sub_f32_e32 v106, v190, v198
	v_sub_f32_e32 v107, v191, v199
	v_cvt_pk_bf16_f32 v108, v108, v109
	v_cvt_pk_bf16_f32 v109, v110, v111
	v_cvt_pk_bf16_f32 v110, v104, v105
	v_cvt_pk_bf16_f32 v111, v106, v107
	global_store_dwordx4 v[176:177], v[108:111], off
	v_pk_mul_f32 v[100:101], v[100:101], v[130:131] op_sel_hi:[1,0]
	v_pk_mul_f32 v[102:103], v[102:103], v[130:131] op_sel_hi:[1,0]
	v_pk_mul_f32 v[96:97], v[96:97], v[130:131] op_sel_hi:[1,0]
	v_pk_mul_f32 v[98:99], v[98:99], v[130:131] op_sel_hi:[1,0]
	v_mul_f32_e32 v184, 0xbfb8aa3b, v100
	v_mul_f32_e32 v185, 0xbfb8aa3b, v101
	v_mul_f32_e32 v186, 0xbfb8aa3b, v102
	v_mul_f32_e32 v187, 0xbfb8aa3b, v103
	v_mul_f32_e32 v188, 0xbfb8aa3b, v96
	v_mul_f32_e32 v189, 0xbfb8aa3b, v97
	v_mul_f32_e32 v190, 0xbfb8aa3b, v98
	v_mul_f32_e32 v191, 0xbfb8aa3b, v99
	v_exp_f32_e32 v184, v184
	v_exp_f32_e32 v185, v185
	v_exp_f32_e32 v186, v186
	v_exp_f32_e32 v187, v187
	v_exp_f32_e32 v188, v188
	v_exp_f32_e32 v189, v189
	v_exp_f32_e32 v190, v190
	v_exp_f32_e32 v191, v191
	v_sub_f32_e32 v192, 1.0, v218
	v_sub_f32_e32 v193, 1.0, v219
	v_sub_f32_e32 v194, 1.0, v220
	v_sub_f32_e32 v195, 1.0, v221
	v_sub_f32_e32 v196, 1.0, v222
	v_sub_f32_e32 v197, 1.0, v223
	v_sub_f32_e32 v198, 1.0, v224
	v_sub_f32_e32 v199, 1.0, v225
	v_add_f32_e32 v184, 1.0, v184
	v_add_f32_e32 v185, 1.0, v185
	v_add_f32_e32 v186, 1.0, v186
	v_add_f32_e32 v187, 1.0, v187
	v_add_f32_e32 v188, 1.0, v188
	v_add_f32_e32 v189, 1.0, v189
	v_add_f32_e32 v190, 1.0, v190
	v_add_f32_e32 v191, 1.0, v191
	v_rcp_f32_e32 v184, v184
	v_rcp_f32_e32 v185, v185
	v_rcp_f32_e32 v186, v186
	v_rcp_f32_e32 v187, v187
	v_rcp_f32_e32 v188, v188
	v_rcp_f32_e32 v189, v189
	v_rcp_f32_e32 v190, v190
	v_rcp_f32_e32 v191, v191
	v_fma_f32 v200, v184, v192, v218
	v_fma_f32 v201, v185, v193, v219
	v_fma_f32 v202, v186, v194, v220
	v_fma_f32 v203, v187, v195, v221
	v_fma_f32 v204, v188, v196, v222
	v_fma_f32 v205, v189, v197, v223
	v_fma_f32 v206, v190, v198, v224
	v_fma_f32 v207, v191, v199, v225
	v_cmp_gt_f32_e64 vcc, s35, v200
	v_cmp_gt_f32_e64 s[38:39], s35, v201
	v_cmp_gt_f32_e64 s[48:49], s35, v202
	v_cmp_gt_f32_e64 s[50:51], s35, v203
	v_cndmask_b32_e64 v184, 0, 32, vcc
	v_cndmask_b32_e64 v185, 0, 32, s[38:39]
	v_cndmask_b32_e64 v186, 0, 32, s[48:49]
	v_cndmask_b32_e64 v187, 0, 32, s[50:51]
	v_cndmask_b32_e64 v192, 0, v214, vcc
	v_cndmask_b32_e64 v193, 0, v214, s[38:39]
	v_cndmask_b32_e64 v194, 0, v214, s[48:49]
	v_cndmask_b32_e64 v195, 0, v214, s[50:51]
	v_cmp_gt_f32_e64 vcc, s35, v204
	v_cmp_gt_f32_e64 s[38:39], s35, v205
	v_cmp_gt_f32_e64 s[48:49], s35, v206
	v_cmp_gt_f32_e64 s[50:51], s35, v207
	v_cndmask_b32_e64 v188, 0, 32, vcc
	v_cndmask_b32_e64 v189, 0, 32, s[38:39]
	v_cndmask_b32_e64 v190, 0, 32, s[48:49]
	v_cndmask_b32_e64 v191, 0, 32, s[50:51]
	v_cndmask_b32_e64 v196, 0, v214, vcc
	v_cndmask_b32_e64 v197, 0, v214, s[38:39]
	v_cndmask_b32_e64 v198, 0, v214, s[48:49]
	v_cndmask_b32_e64 v199, 0, v214, s[50:51]
	v_ldexp_f32 v184, v200, v184
	v_ldexp_f32 v185, v201, v185
	v_ldexp_f32 v186, v202, v186
	v_ldexp_f32 v187, v203, v187
	v_ldexp_f32 v188, v204, v188
	v_ldexp_f32 v189, v205, v189
	v_ldexp_f32 v190, v206, v190
	v_ldexp_f32 v191, v207, v191
	v_log_f32_e32 v184, v184
	v_log_f32_e32 v185, v185
	v_log_f32_e32 v186, v186
	v_log_f32_e32 v187, v187
	v_log_f32_e32 v188, v188
	v_log_f32_e32 v189, v189
	v_log_f32_e32 v190, v190
	v_log_f32_e32 v191, v191
	v_mul_f32_e32 v200, 0x3f317217, v184
	v_mul_f32_e32 v201, 0x3f317217, v185
	v_mul_f32_e32 v202, 0x3f317217, v186
	v_mul_f32_e32 v203, 0x3f317217, v187
	v_mul_f32_e32 v204, 0x3f317217, v188
	v_mul_f32_e32 v205, 0x3f317217, v189
	v_mul_f32_e32 v206, 0x3f317217, v190
	v_mul_f32_e32 v207, 0x3f317217, v191
	v_fma_f32 v200, v184, s13, -v200
	v_fma_f32 v201, v185, s13, -v201
	v_fma_f32 v202, v186, s13, -v202
	v_fma_f32 v203, v187, s13, -v203
	v_fma_f32 v204, v188, s13, -v204
	v_fma_f32 v205, v189, s13, -v205
	v_fma_f32 v206, v190, s13, -v206
	v_fma_f32 v207, v191, s13, -v207
	v_fmac_f32_e32 v200, 0x3377d1cf, v184
	v_fmac_f32_e32 v201, 0x3377d1cf, v185
	v_fmac_f32_e32 v202, 0x3377d1cf, v186
	v_fmac_f32_e32 v203, 0x3377d1cf, v187
	v_fmac_f32_e32 v204, 0x3377d1cf, v188
	v_fmac_f32_e32 v205, 0x3377d1cf, v189
	v_fmac_f32_e32 v206, 0x3377d1cf, v190
	v_fmac_f32_e32 v207, 0x3377d1cf, v191
	v_fmac_f32_e32 v200, 0x3f317217, v184
	v_fmac_f32_e32 v201, 0x3f317217, v185
	v_fmac_f32_e32 v202, 0x3f317217, v186
	v_fmac_f32_e32 v203, 0x3f317217, v187
	v_fmac_f32_e32 v204, 0x3f317217, v188
	v_fmac_f32_e32 v205, 0x3f317217, v189
	v_fmac_f32_e32 v206, 0x3f317217, v190
	v_fmac_f32_e32 v207, 0x3f317217, v191
	v_cmp_lt_f32_e64 vcc, |v184|, s36
	v_cmp_lt_f32_e64 s[38:39], |v185|, s36
	v_cmp_lt_f32_e64 s[48:49], |v186|, s36
	v_cmp_lt_f32_e64 s[50:51], |v187|, s36
	v_cndmask_b32_e64 v184, v184, v200, vcc
	v_cndmask_b32_e64 v185, v185, v201, s[38:39]
	v_cndmask_b32_e64 v186, v186, v202, s[48:49]
	v_cndmask_b32_e64 v187, v187, v203, s[50:51]
	v_cmp_lt_f32_e64 vcc, |v188|, s36
	v_cmp_lt_f32_e64 s[38:39], |v189|, s36
	v_cmp_lt_f32_e64 s[48:49], |v190|, s36
	v_cmp_lt_f32_e64 s[50:51], |v191|, s36
; __device__ __forceinline__ unsigned cvt_pk_bf16(float lo, float hi) { unsigned r; asm volatile("v_cvt_pk_bf16_f32 %0, %1, %2" : "=v"(r) : "v"(lo), "v"(hi)); return r; }
; __device__ __forceinline__ float silu_f(float v) { return v * __builtin_amdgcn_rcpf(1.f + __expf(-v)); }
;     __device__ __forceinline__ void operator()(const f32x4 (&acc)[2][2][4][2], const Unit& u, int wr, int wc, int fr, int fq, int ui, PG8_LAS unsigned char* lds) const {
;     ...
;                     f32x4 v[2] = {acc[ai][bj][m][0] * rs, acc[ai][bj][m][1] * rs};
;                     if (ksum) { csum[bj][0] += v[0]; csum[bj][1] += v[1]; }
; #pragma unroll
;                     for (int n = 0; n < 2; ++n) {
;                         f32x4 lbv = (f32x4){0.f, 0.f, 0.f, 0.f};
;                         if (act == 2) lbv = *(const f32x4*)(lb + (col0 - 1024) + bj * HALF + 4 * n);
; #pragma unroll
;                         for (int e = 0; e < 4; ++e) {
;                             float x = v[n][e];
;                             if (act == 1) x = silu_f(x);
;                             else if (act == 2) { const float l = lbv[e]; x = __logf(l + (1.f - l) * __builtin_amdgcn_rcpf(1.f + __expf(-x))); }
;                             else if (act == 3) { x = fmaxf(x, 0.f); x = x * x; }
;                             v[n][e] = x;
;                         }
;                     }
;                     u32x4 w; w.x = cvt_pk_bf16(v[0][0], v[0][1]); w.y = cvt_pk_bf16(v[0][2], v[0][3]); w.z = cvt_pk_bf16(v[1][0], v[1][1]); w.w = cvt_pk_bf16(v[1][2], v[1][3]);
;                     *(u32x4*)(rowp + bj * HALF) = w;
	v_cndmask_b32_e64 v188, v188, v204, vcc
	v_cndmask_b32_e64 v189, v189, v205, s[38:39]
	v_cndmask_b32_e64 v190, v190, v206, s[48:49]
	v_cndmask_b32_e64 v191, v191, v207, s[50:51]
	v_sub_f32_e32 v100, v184, v192
	v_sub_f32_e32 v101, v185, v193
	v_sub_f32_e32 v102, v186, v194
	v_sub_f32_e32 v103, v187, v195
	v_sub_f32_e32 v96, v188, v196
	v_sub_f32_e32 v97, v189, v197
	v_sub_f32_e32 v98, v190, v198
	v_sub_f32_e32 v99, v191, v199
	v_cvt_pk_bf16_f32 v100, v100, v101
	v_cvt_pk_bf16_f32 v101, v102, v103
	v_cvt_pk_bf16_f32 v102, v96, v97
	v_cvt_pk_bf16_f32 v103, v98, v99
	global_store_dwordx4 v[176:177], v[100:103], off offset:256
	v_lshl_add_u64 v[162:163], v[176:177], 0, s[46:47]
	v_pk_mul_f32 v[92:93], v[92:93], v[144:145] op_sel_hi:[1,0]
	v_pk_mul_f32 v[94:95], v[94:95], v[144:145] op_sel_hi:[1,0]
	v_pk_mul_f32 v[88:89], v[88:89], v[144:145] op_sel_hi:[1,0]
	v_pk_mul_f32 v[90:91], v[90:91], v[144:145] op_sel_hi:[1,0]
	v_mul_f32_e32 v184, 0xbfb8aa3b, v92
	v_mul_f32_e32 v185, 0xbfb8aa3b, v93
	v_mul_f32_e32 v186, 0xbfb8aa3b, v94
	v_mul_f32_e32 v187, 0xbfb8aa3b, v95
	v_mul_f32_e32 v188, 0xbfb8aa3b, v88
	v_mul_f32_e32 v189, 0xbfb8aa3b, v89
	v_mul_f32_e32 v190, 0xbfb8aa3b, v90
	v_mul_f32_e32 v191, 0xbfb8aa3b, v91
	v_exp_f32_e32 v184, v184
	v_exp_f32_e32 v185, v185
	v_exp_f32_e32 v186, v186
	v_exp_f32_e32 v187, v187
	v_exp_f32_e32 v188, v188
	v_exp_f32_e32 v189, v189
	v_exp_f32_e32 v190, v190
	v_exp_f32_e32 v191, v191
	v_sub_f32_e32 v192, 1.0, v152
	v_sub_f32_e32 v193, 1.0, v153
	v_sub_f32_e32 v194, 1.0, v154
	v_sub_f32_e32 v195, 1.0, v155
	v_sub_f32_e32 v196, 1.0, v180
	v_sub_f32_e32 v197, 1.0, v181
	v_sub_f32_e32 v198, 1.0, v182
	v_sub_f32_e32 v199, 1.0, v183
	v_add_f32_e32 v184, 1.0, v184
	v_add_f32_e32 v185, 1.0, v185
	v_add_f32_e32 v186, 1.0, v186
	v_add_f32_e32 v187, 1.0, v187
	v_add_f32_e32 v188, 1.0, v188
	v_add_f32_e32 v189, 1.0, v189
	v_add_f32_e32 v190, 1.0, v190
	v_add_f32_e32 v191, 1.0, v191
	v_rcp_f32_e32 v184, v184
	v_rcp_f32_e32 v185, v185
	v_rcp_f32_e32 v186, v186
	v_rcp_f32_e32 v187, v187
	v_rcp_f32_e32 v188, v188
	v_rcp_f32_e32 v189, v189
	v_rcp_f32_e32 v190, v190
	v_rcp_f32_e32 v191, v191
	v_fma_f32 v200, v184, v192, v152
	v_fma_f32 v201, v185, v193, v153
	v_fma_f32 v202, v186, v194, v154
	v_fma_f32 v203, v187, v195, v155
	v_fma_f32 v204, v188, v196, v180
	v_fma_f32 v205, v189, v197, v181
	v_fma_f32 v206, v190, v198, v182
	v_fma_f32 v207, v191, v199, v183
	v_cmp_gt_f32_e64 vcc, s35, v200
	v_cmp_gt_f32_e64 s[38:39], s35, v201
	v_cmp_gt_f32_e64 s[48:49], s35, v202
	v_cmp_gt_f32_e64 s[50:51], s35, v203
	v_cndmask_b32_e64 v184, 0, 32, vcc
	v_cndmask_b32_e64 v185, 0, 32, s[38:39]
	v_cndmask_b32_e64 v186, 0, 32, s[48:49]
	v_cndmask_b32_e64 v187, 0, 32, s[50:51]
	v_cndmask_b32_e64 v192, 0, v214, vcc
	v_cndmask_b32_e64 v193, 0, v214, s[38:39]
	v_cndmask_b32_e64 v194, 0, v214, s[48:49]
	v_cndmask_b32_e64 v195, 0, v214, s[50:51]
	v_cmp_gt_f32_e64 vcc, s35, v204
	v_cmp_gt_f32_e64 s[38:39], s35, v205
	v_cmp_gt_f32_e64 s[48:49], s35, v206
	v_cmp_gt_f32_e64 s[50:51], s35, v207
	v_cndmask_b32_e64 v188, 0, 32, vcc
	v_cndmask_b32_e64 v189, 0, 32, s[38:39]
	v_cndmask_b32_e64 v190, 0, 32, s[48:49]
	v_cndmask_b32_e64 v191, 0, 32, s[50:51]
	v_cndmask_b32_e64 v196, 0, v214, vcc
	v_cndmask_b32_e64 v197, 0, v214, s[38:39]
	v_cndmask_b32_e64 v198, 0, v214, s[48:49]
	v_cndmask_b32_e64 v199, 0, v214, s[50:51]
	v_ldexp_f32 v184, v200, v184
	v_ldexp_f32 v185, v201, v185
	v_ldexp_f32 v186, v202, v186
	v_ldexp_f32 v187, v203, v187
	v_ldexp_f32 v188, v204, v188
	v_ldexp_f32 v189, v205, v189
	v_ldexp_f32 v190, v206, v190
	v_ldexp_f32 v191, v207, v191
	v_log_f32_e32 v184, v184
	v_log_f32_e32 v185, v185
	v_log_f32_e32 v186, v186
	v_log_f32_e32 v187, v187
	v_log_f32_e32 v188, v188
	v_log_f32_e32 v189, v189
	v_log_f32_e32 v190, v190
	v_log_f32_e32 v191, v191
	v_mul_f32_e32 v200, 0x3f317217, v184
	v_mul_f32_e32 v201, 0x3f317217, v185
	v_mul_f32_e32 v202, 0x3f317217, v186
	v_mul_f32_e32 v203, 0x3f317217, v187
	v_mul_f32_e32 v204, 0x3f317217, v188
	v_mul_f32_e32 v205, 0x3f317217, v189
	v_mul_f32_e32 v206, 0x3f317217, v190
	v_mul_f32_e32 v207, 0x3f317217, v191
	v_fma_f32 v200, v184, s13, -v200
	v_fma_f32 v201, v185, s13, -v201
	v_fma_f32 v202, v186, s13, -v202
	v_fma_f32 v203, v187, s13, -v203
	v_fma_f32 v204, v188, s13, -v204
	v_fma_f32 v205, v189, s13, -v205
	v_fma_f32 v206, v190, s13, -v206
	v_fma_f32 v207, v191, s13, -v207
	v_fmac_f32_e32 v200, 0x3377d1cf, v184
	v_fmac_f32_e32 v201, 0x3377d1cf, v185
	v_fmac_f32_e32 v202, 0x3377d1cf, v186
	v_fmac_f32_e32 v203, 0x3377d1cf, v187
	v_fmac_f32_e32 v204, 0x3377d1cf, v188
	v_fmac_f32_e32 v205, 0x3377d1cf, v189
	v_fmac_f32_e32 v206, 0x3377d1cf, v190
	v_fmac_f32_e32 v207, 0x3377d1cf, v191
	v_fmac_f32_e32 v200, 0x3f317217, v184
	v_fmac_f32_e32 v201, 0x3f317217, v185
	v_fmac_f32_e32 v202, 0x3f317217, v186
	v_fmac_f32_e32 v203, 0x3f317217, v187
	v_fmac_f32_e32 v204, 0x3f317217, v188
	v_fmac_f32_e32 v205, 0x3f317217, v189
	v_fmac_f32_e32 v206, 0x3f317217, v190
	v_fmac_f32_e32 v207, 0x3f317217, v191
	v_cmp_lt_f32_e64 vcc, |v184|, s36
	v_cmp_lt_f32_e64 s[38:39], |v185|, s36
	v_cmp_lt_f32_e64 s[48:49], |v186|, s36
	v_cmp_lt_f32_e64 s[50:51], |v187|, s36
	v_cndmask_b32_e64 v184, v184, v200, vcc
	v_cndmask_b32_e64 v185, v185, v201, s[38:39]
	v_cndmask_b32_e64 v186, v186, v202, s[48:49]
	v_cndmask_b32_e64 v187, v187, v203, s[50:51]
	v_cmp_lt_f32_e64 vcc, |v188|, s36
	v_cmp_lt_f32_e64 s[38:39], |v189|, s36
	v_cmp_lt_f32_e64 s[48:49], |v190|, s36
	v_cmp_lt_f32_e64 s[50:51], |v191|, s36
	v_cndmask_b32_e64 v188, v188, v204, vcc
	v_cndmask_b32_e64 v189, v189, v205, s[38:39]
	v_cndmask_b32_e64 v190, v190, v206, s[48:49]
; __device__ __forceinline__ unsigned cvt_pk_bf16(float lo, float hi) { unsigned r; asm volatile("v_cvt_pk_bf16_f32 %0, %1, %2" : "=v"(r) : "v"(lo), "v"(hi)); return r; }
; __device__ __forceinline__ float silu_f(float v) { return v * __builtin_amdgcn_rcpf(1.f + __expf(-v)); }
;     __device__ __forceinline__ void operator()(const f32x4 (&acc)[2][2][4][2], const Unit& u, int wr, int wc, int fr, int fq, int ui, PG8_LAS unsigned char* lds) const {
;     ...
;                     f32x4 v[2] = {acc[ai][bj][m][0] * rs, acc[ai][bj][m][1] * rs};
;                     if (ksum) { csum[bj][0] += v[0]; csum[bj][1] += v[1]; }
; #pragma unroll
;                     for (int n = 0; n < 2; ++n) {
;                         f32x4 lbv = (f32x4){0.f, 0.f, 0.f, 0.f};
;                         if (act == 2) lbv = *(const f32x4*)(lb + (col0 - 1024) + bj * HALF + 4 * n);
; #pragma unroll
;                         for (int e = 0; e < 4; ++e) {
;                             float x = v[n][e];
;                             if (act == 1) x = silu_f(x);
;                             else if (act == 2) { const float l = lbv[e]; x = __logf(l + (1.f - l) * __builtin_amdgcn_rcpf(1.f + __expf(-x))); }
;                             else if (act == 3) { x = fmaxf(x, 0.f); x = x * x; }
;                             v[n][e] = x;
;                         }
;                     }
;                     u32x4 w; w.x = cvt_pk_bf16(v[0][0], v[0][1]); w.y = cvt_pk_bf16(v[0][2], v[0][3]); w.z = cvt_pk_bf16(v[1][0], v[1][1]); w.w = cvt_pk_bf16(v[1][2], v[1][3]);
;                     *(u32x4*)(rowp + bj * HALF) = w;
	v_cndmask_b32_e64 v191, v191, v207, s[50:51]
	v_sub_f32_e32 v92, v184, v192
	v_sub_f32_e32 v93, v185, v193
	v_sub_f32_e32 v94, v186, v194
	v_sub_f32_e32 v95, v187, v195
	v_sub_f32_e32 v88, v188, v196
	v_sub_f32_e32 v89, v189, v197
	v_sub_f32_e32 v90, v190, v198
	v_sub_f32_e32 v91, v191, v199
	v_cvt_pk_bf16_f32 v92, v92, v93
	v_cvt_pk_bf16_f32 v93, v94, v95
	v_cvt_pk_bf16_f32 v94, v88, v89
	v_cvt_pk_bf16_f32 v95, v90, v91
	global_store_dwordx4 v[162:163], v[92:95], off
	v_pk_mul_f32 v[84:85], v[84:85], v[144:145] op_sel_hi:[1,0]
	v_pk_mul_f32 v[86:87], v[86:87], v[144:145] op_sel_hi:[1,0]
	v_pk_mul_f32 v[80:81], v[80:81], v[144:145] op_sel_hi:[1,0]
	v_pk_mul_f32 v[82:83], v[82:83], v[144:145] op_sel_hi:[1,0]
	v_mul_f32_e32 v184, 0xbfb8aa3b, v84
	v_mul_f32_e32 v185, 0xbfb8aa3b, v85
	v_mul_f32_e32 v186, 0xbfb8aa3b, v86
	v_mul_f32_e32 v187, 0xbfb8aa3b, v87
	v_mul_f32_e32 v188, 0xbfb8aa3b, v80
	v_mul_f32_e32 v189, 0xbfb8aa3b, v81
	v_mul_f32_e32 v190, 0xbfb8aa3b, v82
	v_mul_f32_e32 v191, 0xbfb8aa3b, v83
	v_exp_f32_e32 v184, v184
	v_exp_f32_e32 v185, v185
	v_exp_f32_e32 v186, v186
	v_exp_f32_e32 v187, v187
	v_exp_f32_e32 v188, v188
	v_exp_f32_e32 v189, v189
	v_exp_f32_e32 v190, v190
	v_exp_f32_e32 v191, v191
	v_sub_f32_e32 v192, 1.0, v218
	v_sub_f32_e32 v193, 1.0, v219
	v_sub_f32_e32 v194, 1.0, v220
	v_sub_f32_e32 v195, 1.0, v221
	v_sub_f32_e32 v196, 1.0, v222
	v_sub_f32_e32 v197, 1.0, v223
	v_sub_f32_e32 v198, 1.0, v224
	v_sub_f32_e32 v199, 1.0, v225
	v_add_f32_e32 v184, 1.0, v184
	v_add_f32_e32 v185, 1.0, v185
	v_add_f32_e32 v186, 1.0, v186
	v_add_f32_e32 v187, 1.0, v187
	v_add_f32_e32 v188, 1.0, v188
	v_add_f32_e32 v189, 1.0, v189
	v_add_f32_e32 v190, 1.0, v190
	v_add_f32_e32 v191, 1.0, v191
	v_rcp_f32_e32 v184, v184
	v_rcp_f32_e32 v185, v185
	v_rcp_f32_e32 v186, v186
	v_rcp_f32_e32 v187, v187
	v_rcp_f32_e32 v188, v188
	v_rcp_f32_e32 v189, v189
	v_rcp_f32_e32 v190, v190
	v_rcp_f32_e32 v191, v191
	v_fma_f32 v200, v184, v192, v218
	v_fma_f32 v201, v185, v193, v219
	v_fma_f32 v202, v186, v194, v220
	v_fma_f32 v203, v187, v195, v221
	v_fma_f32 v204, v188, v196, v222
	v_fma_f32 v205, v189, v197, v223
	v_fma_f32 v206, v190, v198, v224
	v_fma_f32 v207, v191, v199, v225
	v_cmp_gt_f32_e64 vcc, s35, v200
	v_cmp_gt_f32_e64 s[38:39], s35, v201
	v_cmp_gt_f32_e64 s[48:49], s35, v202
	v_cmp_gt_f32_e64 s[50:51], s35, v203
	v_cndmask_b32_e64 v184, 0, 32, vcc
	v_cndmask_b32_e64 v185, 0, 32, s[38:39]
	v_cndmask_b32_e64 v186, 0, 32, s[48:49]
	v_cndmask_b32_e64 v187, 0, 32, s[50:51]
	v_cndmask_b32_e64 v192, 0, v214, vcc
	v_cndmask_b32_e64 v193, 0, v214, s[38:39]
	v_cndmask_b32_e64 v194, 0, v214, s[48:49]
	v_cndmask_b32_e64 v195, 0, v214, s[50:51]
	v_cmp_gt_f32_e64 vcc, s35, v204
	v_cmp_gt_f32_e64 s[38:39], s35, v205
	v_cmp_gt_f32_e64 s[48:49], s35, v206
	v_cmp_gt_f32_e64 s[50:51], s35, v207
	v_cndmask_b32_e64 v188, 0, 32, vcc
	v_cndmask_b32_e64 v189, 0, 32, s[38:39]
	v_cndmask_b32_e64 v190, 0, 32, s[48:49]
	v_cndmask_b32_e64 v191, 0, 32, s[50:51]
	v_cndmask_b32_e64 v196, 0, v214, vcc
	v_cndmask_b32_e64 v197, 0, v214, s[38:39]
	v_cndmask_b32_e64 v198, 0, v214, s[48:49]
	v_cndmask_b32_e64 v199, 0, v214, s[50:51]
	v_ldexp_f32 v184, v200, v184
	v_ldexp_f32 v185, v201, v185
	v_ldexp_f32 v186, v202, v186
	v_ldexp_f32 v187, v203, v187
	v_ldexp_f32 v188, v204, v188
	v_ldexp_f32 v189, v205, v189
	v_ldexp_f32 v190, v206, v190
	v_ldexp_f32 v191, v207, v191
	v_log_f32_e32 v184, v184
	v_log_f32_e32 v185, v185
	v_log_f32_e32 v186, v186
	v_log_f32_e32 v187, v187
	v_log_f32_e32 v188, v188
	v_log_f32_e32 v189, v189
	v_log_f32_e32 v190, v190
	v_log_f32_e32 v191, v191
	v_mul_f32_e32 v200, 0x3f317217, v184
	v_mul_f32_e32 v201, 0x3f317217, v185
	v_mul_f32_e32 v202, 0x3f317217, v186
	v_mul_f32_e32 v203, 0x3f317217, v187
	v_mul_f32_e32 v204, 0x3f317217, v188
	v_mul_f32_e32 v205, 0x3f317217, v189
	v_mul_f32_e32 v206, 0x3f317217, v190
	v_mul_f32_e32 v207, 0x3f317217, v191
	v_fma_f32 v200, v184, s13, -v200
	v_fma_f32 v201, v185, s13, -v201
	v_fma_f32 v202, v186, s13, -v202
	v_fma_f32 v203, v187, s13, -v203
	v_fma_f32 v204, v188, s13, -v204
	v_fma_f32 v205, v189, s13, -v205
	v_fma_f32 v206, v190, s13, -v206
	v_fma_f32 v207, v191, s13, -v207
	v_fmac_f32_e32 v200, 0x3377d1cf, v184
	v_fmac_f32_e32 v201, 0x3377d1cf, v185
	v_fmac_f32_e32 v202, 0x3377d1cf, v186
	v_fmac_f32_e32 v203, 0x3377d1cf, v187
	v_fmac_f32_e32 v204, 0x3377d1cf, v188
	v_fmac_f32_e32 v205, 0x3377d1cf, v189
	v_fmac_f32_e32 v206, 0x3377d1cf, v190
	v_fmac_f32_e32 v207, 0x3377d1cf, v191
	v_fmac_f32_e32 v200, 0x3f317217, v184
	v_fmac_f32_e32 v201, 0x3f317217, v185
	v_fmac_f32_e32 v202, 0x3f317217, v186
	v_fmac_f32_e32 v203, 0x3f317217, v187
	v_fmac_f32_e32 v204, 0x3f317217, v188
	v_fmac_f32_e32 v205, 0x3f317217, v189
	v_fmac_f32_e32 v206, 0x3f317217, v190
	v_fmac_f32_e32 v207, 0x3f317217, v191
	v_cmp_lt_f32_e64 vcc, |v184|, s36
	v_cmp_lt_f32_e64 s[38:39], |v185|, s36
	v_cmp_lt_f32_e64 s[48:49], |v186|, s36
	v_cmp_lt_f32_e64 s[50:51], |v187|, s36
	v_cndmask_b32_e64 v184, v184, v200, vcc
	v_cndmask_b32_e64 v185, v185, v201, s[38:39]
	v_cndmask_b32_e64 v186, v186, v202, s[48:49]
	v_cndmask_b32_e64 v187, v187, v203, s[50:51]
	v_cmp_lt_f32_e64 vcc, |v188|, s36
	v_cmp_lt_f32_e64 s[38:39], |v189|, s36
	v_cmp_lt_f32_e64 s[48:49], |v190|, s36
	v_cmp_lt_f32_e64 s[50:51], |v191|, s36
	v_cndmask_b32_e64 v188, v188, v204, vcc
	v_cndmask_b32_e64 v189, v189, v205, s[38:39]
	v_cndmask_b32_e64 v190, v190, v206, s[48:49]
	v_cndmask_b32_e64 v191, v191, v207, s[50:51]
	v_sub_f32_e32 v84, v184, v192
	v_sub_f32_e32 v85, v185, v193
	v_sub_f32_e32 v86, v186, v194
	v_sub_f32_e32 v87, v187, v195
	v_sub_f32_e32 v80, v188, v196
	v_sub_f32_e32 v81, v189, v197
; __device__ __forceinline__ unsigned cvt_pk_bf16(float lo, float hi) { unsigned r; asm volatile("v_cvt_pk_bf16_f32 %0, %1, %2" : "=v"(r) : "v"(lo), "v"(hi)); return r; }
; __device__ __forceinline__ float silu_f(float v) { return v * __builtin_amdgcn_rcpf(1.f + __expf(-v)); }
;     __device__ __forceinline__ void operator()(const f32x4 (&acc)[2][2][4][2], const Unit& u, int wr, int wc, int fr, int fq, int ui, PG8_LAS unsigned char* lds) const {
;     ...
;                     f32x4 v[2] = {acc[ai][bj][m][0] * rs, acc[ai][bj][m][1] * rs};
;                     if (ksum) { csum[bj][0] += v[0]; csum[bj][1] += v[1]; }
; #pragma unroll
;                     for (int n = 0; n < 2; ++n) {
;                         f32x4 lbv = (f32x4){0.f, 0.f, 0.f, 0.f};
;                         if (act == 2) lbv = *(const f32x4*)(lb + (col0 - 1024) + bj * HALF + 4 * n);
; #pragma unroll
;                         for (int e = 0; e < 4; ++e) {
;                             float x = v[n][e];
;                             if (act == 1) x = silu_f(x);
;                             else if (act == 2) { const float l = lbv[e]; x = __logf(l + (1.f - l) * __builtin_amdgcn_rcpf(1.f + __expf(-x))); }
;                             else if (act == 3) { x = fmaxf(x, 0.f); x = x * x; }
;                             v[n][e] = x;
;                         }
;                     }
;                     u32x4 w; w.x = cvt_pk_bf16(v[0][0], v[0][1]); w.y = cvt_pk_bf16(v[0][2], v[0][3]); w.z = cvt_pk_bf16(v[1][0], v[1][1]); w.w = cvt_pk_bf16(v[1][2], v[1][3]);
;                     *(u32x4*)(rowp + bj * HALF) = w;
	v_sub_f32_e32 v82, v190, v198
	v_sub_f32_e32 v83, v191, v199
	v_cvt_pk_bf16_f32 v84, v84, v85
	v_cvt_pk_bf16_f32 v85, v86, v87
	v_cvt_pk_bf16_f32 v86, v80, v81
	v_cvt_pk_bf16_f32 v87, v82, v83
	global_store_dwordx4 v[162:163], v[84:87], off offset:256
	v_lshl_add_u64 v[176:177], v[162:163], 0, s[46:47]
	v_pk_mul_f32 v[76:77], v[76:77], v[146:147] op_sel_hi:[1,0]
	v_pk_mul_f32 v[78:79], v[78:79], v[146:147] op_sel_hi:[1,0]
	v_pk_mul_f32 v[72:73], v[72:73], v[146:147] op_sel_hi:[1,0]
	v_pk_mul_f32 v[74:75], v[74:75], v[146:147] op_sel_hi:[1,0]
	v_mul_f32_e32 v184, 0xbfb8aa3b, v76
	v_mul_f32_e32 v185, 0xbfb8aa3b, v77
	v_mul_f32_e32 v186, 0xbfb8aa3b, v78
	v_mul_f32_e32 v187, 0xbfb8aa3b, v79
	v_mul_f32_e32 v188, 0xbfb8aa3b, v72
	v_mul_f32_e32 v189, 0xbfb8aa3b, v73
	v_mul_f32_e32 v190, 0xbfb8aa3b, v74
	v_mul_f32_e32 v191, 0xbfb8aa3b, v75
	v_exp_f32_e32 v184, v184
	v_exp_f32_e32 v185, v185
	v_exp_f32_e32 v186, v186
	v_exp_f32_e32 v187, v187
	v_exp_f32_e32 v188, v188
	v_exp_f32_e32 v189, v189
	v_exp_f32_e32 v190, v190
	v_exp_f32_e32 v191, v191
	v_sub_f32_e32 v192, 1.0, v152
	v_sub_f32_e32 v193, 1.0, v153
	v_sub_f32_e32 v194, 1.0, v154
	v_sub_f32_e32 v195, 1.0, v155
	v_sub_f32_e32 v196, 1.0, v180
	v_sub_f32_e32 v197, 1.0, v181
	v_sub_f32_e32 v198, 1.0, v182
	v_sub_f32_e32 v199, 1.0, v183
	v_add_f32_e32 v184, 1.0, v184
	v_add_f32_e32 v185, 1.0, v185
	v_add_f32_e32 v186, 1.0, v186
	v_add_f32_e32 v187, 1.0, v187
	v_add_f32_e32 v188, 1.0, v188
	v_add_f32_e32 v189, 1.0, v189
	v_add_f32_e32 v190, 1.0, v190
	v_add_f32_e32 v191, 1.0, v191
	v_rcp_f32_e32 v184, v184
	v_rcp_f32_e32 v185, v185
	v_rcp_f32_e32 v186, v186
	v_rcp_f32_e32 v187, v187
	v_rcp_f32_e32 v188, v188
	v_rcp_f32_e32 v189, v189
	v_rcp_f32_e32 v190, v190
	v_rcp_f32_e32 v191, v191
	v_fma_f32 v200, v184, v192, v152
	v_fma_f32 v201, v185, v193, v153
	v_fma_f32 v202, v186, v194, v154
	v_fma_f32 v203, v187, v195, v155
	v_fma_f32 v204, v188, v196, v180
	v_fma_f32 v205, v189, v197, v181
	v_fma_f32 v206, v190, v198, v182
	v_fma_f32 v207, v191, v199, v183
	v_cmp_gt_f32_e64 vcc, s35, v200
	v_cmp_gt_f32_e64 s[38:39], s35, v201
	v_cmp_gt_f32_e64 s[48:49], s35, v202
	v_cmp_gt_f32_e64 s[50:51], s35, v203
	v_cndmask_b32_e64 v184, 0, 32, vcc
	v_cndmask_b32_e64 v185, 0, 32, s[38:39]
	v_cndmask_b32_e64 v186, 0, 32, s[48:49]
	v_cndmask_b32_e64 v187, 0, 32, s[50:51]
	v_cndmask_b32_e64 v192, 0, v214, vcc
	v_cndmask_b32_e64 v193, 0, v214, s[38:39]
	v_cndmask_b32_e64 v194, 0, v214, s[48:49]
	v_cndmask_b32_e64 v195, 0, v214, s[50:51]
	v_cmp_gt_f32_e64 vcc, s35, v204
	v_cmp_gt_f32_e64 s[38:39], s35, v205
	v_cmp_gt_f32_e64 s[48:49], s35, v206
	v_cmp_gt_f32_e64 s[50:51], s35, v207
	v_cndmask_b32_e64 v188, 0, 32, vcc
	v_cndmask_b32_e64 v189, 0, 32, s[38:39]
	v_cndmask_b32_e64 v190, 0, 32, s[48:49]
	v_cndmask_b32_e64 v191, 0, 32, s[50:51]
	v_cndmask_b32_e64 v196, 0, v214, vcc
	v_cndmask_b32_e64 v197, 0, v214, s[38:39]
	v_cndmask_b32_e64 v198, 0, v214, s[48:49]
	v_cndmask_b32_e64 v199, 0, v214, s[50:51]
	v_ldexp_f32 v184, v200, v184
	v_ldexp_f32 v185, v201, v185
	v_ldexp_f32 v186, v202, v186
	v_ldexp_f32 v187, v203, v187
	v_ldexp_f32 v188, v204, v188
	v_ldexp_f32 v189, v205, v189
	v_ldexp_f32 v190, v206, v190
	v_ldexp_f32 v191, v207, v191
	v_log_f32_e32 v184, v184
	v_log_f32_e32 v185, v185
	v_log_f32_e32 v186, v186
	v_log_f32_e32 v187, v187
	v_log_f32_e32 v188, v188
	v_log_f32_e32 v189, v189
	v_log_f32_e32 v190, v190
	v_log_f32_e32 v191, v191
	v_mul_f32_e32 v200, 0x3f317217, v184
	v_mul_f32_e32 v201, 0x3f317217, v185
	v_mul_f32_e32 v202, 0x3f317217, v186
	v_mul_f32_e32 v203, 0x3f317217, v187
	v_mul_f32_e32 v204, 0x3f317217, v188
	v_mul_f32_e32 v205, 0x3f317217, v189
	v_mul_f32_e32 v206, 0x3f317217, v190
	v_mul_f32_e32 v207, 0x3f317217, v191
	v_fma_f32 v200, v184, s13, -v200
	v_fma_f32 v201, v185, s13, -v201
	v_fma_f32 v202, v186, s13, -v202
	v_fma_f32 v203, v187, s13, -v203
	v_fma_f32 v204, v188, s13, -v204
	v_fma_f32 v205, v189, s13, -v205
	v_fma_f32 v206, v190, s13, -v206
	v_fma_f32 v207, v191, s13, -v207
	v_fmac_f32_e32 v200, 0x3377d1cf, v184
	v_fmac_f32_e32 v201, 0x3377d1cf, v185
	v_fmac_f32_e32 v202, 0x3377d1cf, v186
	v_fmac_f32_e32 v203, 0x3377d1cf, v187
	v_fmac_f32_e32 v204, 0x3377d1cf, v188
	v_fmac_f32_e32 v205, 0x3377d1cf, v189
	v_fmac_f32_e32 v206, 0x3377d1cf, v190
	v_fmac_f32_e32 v207, 0x3377d1cf, v191
	v_fmac_f32_e32 v200, 0x3f317217, v184
	v_fmac_f32_e32 v201, 0x3f317217, v185
	v_fmac_f32_e32 v202, 0x3f317217, v186
	v_fmac_f32_e32 v203, 0x3f317217, v187
	v_fmac_f32_e32 v204, 0x3f317217, v188
	v_fmac_f32_e32 v205, 0x3f317217, v189
	v_fmac_f32_e32 v206, 0x3f317217, v190
	v_fmac_f32_e32 v207, 0x3f317217, v191
	v_cmp_lt_f32_e64 vcc, |v184|, s36
	v_cmp_lt_f32_e64 s[38:39], |v185|, s36
	v_cmp_lt_f32_e64 s[48:49], |v186|, s36
	v_cmp_lt_f32_e64 s[50:51], |v187|, s36
	v_cndmask_b32_e64 v184, v184, v200, vcc
	v_cndmask_b32_e64 v185, v185, v201, s[38:39]
	v_cndmask_b32_e64 v186, v186, v202, s[48:49]
	v_cndmask_b32_e64 v187, v187, v203, s[50:51]
	v_cmp_lt_f32_e64 vcc, |v188|, s36
	v_cmp_lt_f32_e64 s[38:39], |v189|, s36
	v_cmp_lt_f32_e64 s[48:49], |v190|, s36
	v_cmp_lt_f32_e64 s[50:51], |v191|, s36
	v_cndmask_b32_e64 v188, v188, v204, vcc
	v_cndmask_b32_e64 v189, v189, v205, s[38:39]
	v_cndmask_b32_e64 v190, v190, v206, s[48:49]
	v_cndmask_b32_e64 v191, v191, v207, s[50:51]
	v_sub_f32_e32 v76, v184, v192
	v_sub_f32_e32 v77, v185, v193
	v_sub_f32_e32 v78, v186, v194
	v_sub_f32_e32 v79, v187, v195
	v_sub_f32_e32 v72, v188, v196
	v_sub_f32_e32 v73, v189, v197
	v_sub_f32_e32 v74, v190, v198
	v_sub_f32_e32 v75, v191, v199
	v_cvt_pk_bf16_f32 v76, v76, v77
	v_cvt_pk_bf16_f32 v77, v78, v79
	v_cvt_pk_bf16_f32 v78, v72, v73
; __device__ __forceinline__ unsigned cvt_pk_bf16(float lo, float hi) { unsigned r; asm volatile("v_cvt_pk_bf16_f32 %0, %1, %2" : "=v"(r) : "v"(lo), "v"(hi)); return r; }
; __device__ __forceinline__ float silu_f(float v) { return v * __builtin_amdgcn_rcpf(1.f + __expf(-v)); }
;     __device__ __forceinline__ void operator()(const f32x4 (&acc)[2][2][4][2], const Unit& u, int wr, int wc, int fr, int fq, int ui, PG8_LAS unsigned char* lds) const {
;     ...
;                     f32x4 v[2] = {acc[ai][bj][m][0] * rs, acc[ai][bj][m][1] * rs};
;                     if (ksum) { csum[bj][0] += v[0]; csum[bj][1] += v[1]; }
; #pragma unroll
;                     for (int n = 0; n < 2; ++n) {
;                         f32x4 lbv = (f32x4){0.f, 0.f, 0.f, 0.f};
;                         if (act == 2) lbv = *(const f32x4*)(lb + (col0 - 1024) + bj * HALF + 4 * n);
; #pragma unroll
;                         for (int e = 0; e < 4; ++e) {
;                             float x = v[n][e];
;                             if (act == 1) x = silu_f(x);
;                             else if (act == 2) { const float l = lbv[e]; x = __logf(l + (1.f - l) * __builtin_amdgcn_rcpf(1.f + __expf(-x))); }
;                             else if (act == 3) { x = fmaxf(x, 0.f); x = x * x; }
;                             v[n][e] = x;
;                         }
;                     }
;                     u32x4 w; w.x = cvt_pk_bf16(v[0][0], v[0][1]); w.y = cvt_pk_bf16(v[0][2], v[0][3]); w.z = cvt_pk_bf16(v[1][0], v[1][1]); w.w = cvt_pk_bf16(v[1][2], v[1][3]);
;                     *(u32x4*)(rowp + bj * HALF) = w;
	v_cvt_pk_bf16_f32 v79, v74, v75
	global_store_dwordx4 v[176:177], v[76:79], off
	v_pk_mul_f32 v[68:69], v[68:69], v[146:147] op_sel_hi:[1,0]
	v_pk_mul_f32 v[70:71], v[70:71], v[146:147] op_sel_hi:[1,0]
	v_pk_mul_f32 v[64:65], v[64:65], v[146:147] op_sel_hi:[1,0]
	v_pk_mul_f32 v[66:67], v[66:67], v[146:147] op_sel_hi:[1,0]
	v_mul_f32_e32 v184, 0xbfb8aa3b, v68
	v_mul_f32_e32 v185, 0xbfb8aa3b, v69
	v_mul_f32_e32 v186, 0xbfb8aa3b, v70
	v_mul_f32_e32 v187, 0xbfb8aa3b, v71
	v_mul_f32_e32 v188, 0xbfb8aa3b, v64
	v_mul_f32_e32 v189, 0xbfb8aa3b, v65
	v_mul_f32_e32 v190, 0xbfb8aa3b, v66
	v_mul_f32_e32 v191, 0xbfb8aa3b, v67
	v_exp_f32_e32 v184, v184
	v_exp_f32_e32 v185, v185
	v_exp_f32_e32 v186, v186
	v_exp_f32_e32 v187, v187
	v_exp_f32_e32 v188, v188
	v_exp_f32_e32 v189, v189
	v_exp_f32_e32 v190, v190
	v_exp_f32_e32 v191, v191
	v_sub_f32_e32 v192, 1.0, v218
	v_sub_f32_e32 v193, 1.0, v219
	v_sub_f32_e32 v194, 1.0, v220
	v_sub_f32_e32 v195, 1.0, v221
	v_sub_f32_e32 v196, 1.0, v222
	v_sub_f32_e32 v197, 1.0, v223
	v_sub_f32_e32 v198, 1.0, v224
	v_sub_f32_e32 v199, 1.0, v225
	v_add_f32_e32 v184, 1.0, v184
	v_add_f32_e32 v185, 1.0, v185
	v_add_f32_e32 v186, 1.0, v186
	v_add_f32_e32 v187, 1.0, v187
	v_add_f32_e32 v188, 1.0, v188
	v_add_f32_e32 v189, 1.0, v189
	v_add_f32_e32 v190, 1.0, v190
	v_add_f32_e32 v191, 1.0, v191
	v_rcp_f32_e32 v184, v184
	v_rcp_f32_e32 v185, v185
	v_rcp_f32_e32 v186, v186
	v_rcp_f32_e32 v187, v187
	v_rcp_f32_e32 v188, v188
	v_rcp_f32_e32 v189, v189
	v_rcp_f32_e32 v190, v190
	v_rcp_f32_e32 v191, v191
	v_fma_f32 v200, v184, v192, v218
	v_fma_f32 v201, v185, v193, v219
	v_fma_f32 v202, v186, v194, v220
	v_fma_f32 v203, v187, v195, v221
	v_fma_f32 v204, v188, v196, v222
	v_fma_f32 v205, v189, v197, v223
	v_fma_f32 v206, v190, v198, v224
	v_fma_f32 v207, v191, v199, v225
	v_cmp_gt_f32_e64 vcc, s35, v200
	v_cmp_gt_f32_e64 s[38:39], s35, v201
	v_cmp_gt_f32_e64 s[48:49], s35, v202
	v_cmp_gt_f32_e64 s[50:51], s35, v203
	v_cndmask_b32_e64 v184, 0, 32, vcc
	v_cndmask_b32_e64 v185, 0, 32, s[38:39]
	v_cndmask_b32_e64 v186, 0, 32, s[48:49]
	v_cndmask_b32_e64 v187, 0, 32, s[50:51]
	v_cndmask_b32_e64 v192, 0, v214, vcc
	v_cndmask_b32_e64 v193, 0, v214, s[38:39]
	v_cndmask_b32_e64 v194, 0, v214, s[48:49]
	v_cndmask_b32_e64 v195, 0, v214, s[50:51]
	v_cmp_gt_f32_e64 vcc, s35, v204
	v_cmp_gt_f32_e64 s[38:39], s35, v205
	v_cmp_gt_f32_e64 s[48:49], s35, v206
	v_cmp_gt_f32_e64 s[50:51], s35, v207
	v_cndmask_b32_e64 v188, 0, 32, vcc
	v_cndmask_b32_e64 v189, 0, 32, s[38:39]
	v_cndmask_b32_e64 v190, 0, 32, s[48:49]
	v_cndmask_b32_e64 v191, 0, 32, s[50:51]
	v_cndmask_b32_e64 v196, 0, v214, vcc
	v_cndmask_b32_e64 v197, 0, v214, s[38:39]
	v_cndmask_b32_e64 v198, 0, v214, s[48:49]
	v_cndmask_b32_e64 v199, 0, v214, s[50:51]
	v_ldexp_f32 v184, v200, v184
	v_ldexp_f32 v185, v201, v185
	v_ldexp_f32 v186, v202, v186
	v_ldexp_f32 v187, v203, v187
	v_ldexp_f32 v188, v204, v188
	v_ldexp_f32 v189, v205, v189
	v_ldexp_f32 v190, v206, v190
	v_ldexp_f32 v191, v207, v191
	v_log_f32_e32 v184, v184
	v_log_f32_e32 v185, v185
	v_log_f32_e32 v186, v186
	v_log_f32_e32 v187, v187
	v_log_f32_e32 v188, v188
	v_log_f32_e32 v189, v189
	v_log_f32_e32 v190, v190
	v_log_f32_e32 v191, v191
	v_mul_f32_e32 v200, 0x3f317217, v184
	v_mul_f32_e32 v201, 0x3f317217, v185
	v_mul_f32_e32 v202, 0x3f317217, v186
	v_mul_f32_e32 v203, 0x3f317217, v187
	v_mul_f32_e32 v204, 0x3f317217, v188
	v_mul_f32_e32 v205, 0x3f317217, v189
	v_mul_f32_e32 v206, 0x3f317217, v190
	v_mul_f32_e32 v207, 0x3f317217, v191
	v_fma_f32 v200, v184, s13, -v200
	v_fma_f32 v201, v185, s13, -v201
	v_fma_f32 v202, v186, s13, -v202
	v_fma_f32 v203, v187, s13, -v203
	v_fma_f32 v204, v188, s13, -v204
	v_fma_f32 v205, v189, s13, -v205
	v_fma_f32 v206, v190, s13, -v206
	v_fma_f32 v207, v191, s13, -v207
	v_fmac_f32_e32 v200, 0x3377d1cf, v184
	v_fmac_f32_e32 v201, 0x3377d1cf, v185
	v_fmac_f32_e32 v202, 0x3377d1cf, v186
	v_fmac_f32_e32 v203, 0x3377d1cf, v187
	v_fmac_f32_e32 v204, 0x3377d1cf, v188
	v_fmac_f32_e32 v205, 0x3377d1cf, v189
	v_fmac_f32_e32 v206, 0x3377d1cf, v190
	v_fmac_f32_e32 v207, 0x3377d1cf, v191
	v_fmac_f32_e32 v200, 0x3f317217, v184
	v_fmac_f32_e32 v201, 0x3f317217, v185
	v_fmac_f32_e32 v202, 0x3f317217, v186
	v_fmac_f32_e32 v203, 0x3f317217, v187
	v_fmac_f32_e32 v204, 0x3f317217, v188
	v_fmac_f32_e32 v205, 0x3f317217, v189
	v_fmac_f32_e32 v206, 0x3f317217, v190
	v_fmac_f32_e32 v207, 0x3f317217, v191
	v_cmp_lt_f32_e64 vcc, |v184|, s36
	v_cmp_lt_f32_e64 s[38:39], |v185|, s36
	v_cmp_lt_f32_e64 s[48:49], |v186|, s36
	v_cmp_lt_f32_e64 s[50:51], |v187|, s36
	v_cndmask_b32_e64 v184, v184, v200, vcc
	v_cndmask_b32_e64 v185, v185, v201, s[38:39]
	v_cndmask_b32_e64 v186, v186, v202, s[48:49]
	v_cndmask_b32_e64 v187, v187, v203, s[50:51]
	v_cmp_lt_f32_e64 vcc, |v188|, s36
	v_cmp_lt_f32_e64 s[38:39], |v189|, s36
	v_cmp_lt_f32_e64 s[48:49], |v190|, s36
	v_cmp_lt_f32_e64 s[50:51], |v191|, s36
	v_cndmask_b32_e64 v188, v188, v204, vcc
	v_cndmask_b32_e64 v189, v189, v205, s[38:39]
	v_cndmask_b32_e64 v190, v190, v206, s[48:49]
	v_cndmask_b32_e64 v191, v191, v207, s[50:51]
	v_sub_f32_e32 v68, v184, v192
	v_sub_f32_e32 v69, v185, v193
	v_sub_f32_e32 v70, v186, v194
	v_sub_f32_e32 v71, v187, v195
	v_sub_f32_e32 v64, v188, v196
	v_sub_f32_e32 v65, v189, v197
	v_sub_f32_e32 v66, v190, v198
	v_sub_f32_e32 v67, v191, v199
	v_cvt_pk_bf16_f32 v68, v68, v69
	v_cvt_pk_bf16_f32 v69, v70, v71
	v_cvt_pk_bf16_f32 v70, v64, v65
	v_cvt_pk_bf16_f32 v71, v66, v67
	global_store_dwordx4 v[176:177], v[68:71], off offset:256
	v_lshl_add_u64 v[162:163], v[178:179], 0, 0
	v_pk_mul_f32 v[60:61], v[60:61], v[148:149] op_sel_hi:[1,0]
; __device__ __forceinline__ unsigned cvt_pk_bf16(float lo, float hi) { unsigned r; asm volatile("v_cvt_pk_bf16_f32 %0, %1, %2" : "=v"(r) : "v"(lo), "v"(hi)); return r; }
; __device__ __forceinline__ float silu_f(float v) { return v * __builtin_amdgcn_rcpf(1.f + __expf(-v)); }
;     __device__ __forceinline__ void operator()(const f32x4 (&acc)[2][2][4][2], const Unit& u, int wr, int wc, int fr, int fq, int ui, PG8_LAS unsigned char* lds) const {
;     ...
;                     f32x4 v[2] = {acc[ai][bj][m][0] * rs, acc[ai][bj][m][1] * rs};
;                     if (ksum) { csum[bj][0] += v[0]; csum[bj][1] += v[1]; }
; #pragma unroll
;                     for (int n = 0; n < 2; ++n) {
;                         f32x4 lbv = (f32x4){0.f, 0.f, 0.f, 0.f};
;                         if (act == 2) lbv = *(const f32x4*)(lb + (col0 - 1024) + bj * HALF + 4 * n);
; #pragma unroll
;                         for (int e = 0; e < 4; ++e) {
;                             float x = v[n][e];
;                             if (act == 1) x = silu_f(x);
;                             else if (act == 2) { const float l = lbv[e]; x = __logf(l + (1.f - l) * __builtin_amdgcn_rcpf(1.f + __expf(-x))); }
;                             else if (act == 3) { x = fmaxf(x, 0.f); x = x * x; }
;                             v[n][e] = x;
;                         }
;                     }
;                     u32x4 w; w.x = cvt_pk_bf16(v[0][0], v[0][1]); w.y = cvt_pk_bf16(v[0][2], v[0][3]); w.z = cvt_pk_bf16(v[1][0], v[1][1]); w.w = cvt_pk_bf16(v[1][2], v[1][3]);
;                     *(u32x4*)(rowp + bj * HALF) = w;
	v_pk_mul_f32 v[62:63], v[62:63], v[148:149] op_sel_hi:[1,0]
	v_pk_mul_f32 v[56:57], v[56:57], v[148:149] op_sel_hi:[1,0]
	v_pk_mul_f32 v[58:59], v[58:59], v[148:149] op_sel_hi:[1,0]
	v_mul_f32_e32 v184, 0xbfb8aa3b, v60
	v_mul_f32_e32 v185, 0xbfb8aa3b, v61
	v_mul_f32_e32 v186, 0xbfb8aa3b, v62
	v_mul_f32_e32 v187, 0xbfb8aa3b, v63
	v_mul_f32_e32 v188, 0xbfb8aa3b, v56
	v_mul_f32_e32 v189, 0xbfb8aa3b, v57
	v_mul_f32_e32 v190, 0xbfb8aa3b, v58
	v_mul_f32_e32 v191, 0xbfb8aa3b, v59
	v_exp_f32_e32 v184, v184
	v_exp_f32_e32 v185, v185
	v_exp_f32_e32 v186, v186
	v_exp_f32_e32 v187, v187
	v_exp_f32_e32 v188, v188
	v_exp_f32_e32 v189, v189
	v_exp_f32_e32 v190, v190
	v_exp_f32_e32 v191, v191
	v_sub_f32_e32 v192, 1.0, v152
	v_sub_f32_e32 v193, 1.0, v153
	v_sub_f32_e32 v194, 1.0, v154
	v_sub_f32_e32 v195, 1.0, v155
	v_sub_f32_e32 v196, 1.0, v180
	v_sub_f32_e32 v197, 1.0, v181
	v_sub_f32_e32 v198, 1.0, v182
	v_sub_f32_e32 v199, 1.0, v183
	v_add_f32_e32 v184, 1.0, v184
	v_add_f32_e32 v185, 1.0, v185
	v_add_f32_e32 v186, 1.0, v186
	v_add_f32_e32 v187, 1.0, v187
	v_add_f32_e32 v188, 1.0, v188
	v_add_f32_e32 v189, 1.0, v189
	v_add_f32_e32 v190, 1.0, v190
	v_add_f32_e32 v191, 1.0, v191
	v_rcp_f32_e32 v184, v184
	v_rcp_f32_e32 v185, v185
	v_rcp_f32_e32 v186, v186
	v_rcp_f32_e32 v187, v187
	v_rcp_f32_e32 v188, v188
	v_rcp_f32_e32 v189, v189
	v_rcp_f32_e32 v190, v190
	v_rcp_f32_e32 v191, v191
	v_fma_f32 v200, v184, v192, v152
	v_fma_f32 v201, v185, v193, v153
	v_fma_f32 v202, v186, v194, v154
	v_fma_f32 v203, v187, v195, v155
	v_fma_f32 v204, v188, v196, v180
	v_fma_f32 v205, v189, v197, v181
	v_fma_f32 v206, v190, v198, v182
	v_fma_f32 v207, v191, v199, v183
	v_cmp_gt_f32_e64 vcc, s35, v200
	v_cmp_gt_f32_e64 s[38:39], s35, v201
	v_cmp_gt_f32_e64 s[48:49], s35, v202
	v_cmp_gt_f32_e64 s[50:51], s35, v203
	v_cndmask_b32_e64 v184, 0, 32, vcc
	v_cndmask_b32_e64 v185, 0, 32, s[38:39]
	v_cndmask_b32_e64 v186, 0, 32, s[48:49]
	v_cndmask_b32_e64 v187, 0, 32, s[50:51]
	v_cndmask_b32_e64 v192, 0, v214, vcc
	v_cndmask_b32_e64 v193, 0, v214, s[38:39]
	v_cndmask_b32_e64 v194, 0, v214, s[48:49]
	v_cndmask_b32_e64 v195, 0, v214, s[50:51]
	v_cmp_gt_f32_e64 vcc, s35, v204
	v_cmp_gt_f32_e64 s[38:39], s35, v205
	v_cmp_gt_f32_e64 s[48:49], s35, v206
	v_cmp_gt_f32_e64 s[50:51], s35, v207
	v_cndmask_b32_e64 v188, 0, 32, vcc
	v_cndmask_b32_e64 v189, 0, 32, s[38:39]
	v_cndmask_b32_e64 v190, 0, 32, s[48:49]
	v_cndmask_b32_e64 v191, 0, 32, s[50:51]
	v_cndmask_b32_e64 v196, 0, v214, vcc
	v_cndmask_b32_e64 v197, 0, v214, s[38:39]
	v_cndmask_b32_e64 v198, 0, v214, s[48:49]
	v_cndmask_b32_e64 v199, 0, v214, s[50:51]
	v_ldexp_f32 v184, v200, v184
	v_ldexp_f32 v185, v201, v185
	v_ldexp_f32 v186, v202, v186
	v_ldexp_f32 v187, v203, v187
	v_ldexp_f32 v188, v204, v188
	v_ldexp_f32 v189, v205, v189
	v_ldexp_f32 v190, v206, v190
	v_ldexp_f32 v191, v207, v191
	v_log_f32_e32 v184, v184
	v_log_f32_e32 v185, v185
	v_log_f32_e32 v186, v186
	v_log_f32_e32 v187, v187
	v_log_f32_e32 v188, v188
	v_log_f32_e32 v189, v189
	v_log_f32_e32 v190, v190
	v_log_f32_e32 v191, v191
	v_mul_f32_e32 v200, 0x3f317217, v184
	v_mul_f32_e32 v201, 0x3f317217, v185
	v_mul_f32_e32 v202, 0x3f317217, v186
	v_mul_f32_e32 v203, 0x3f317217, v187
	v_mul_f32_e32 v204, 0x3f317217, v188
	v_mul_f32_e32 v205, 0x3f317217, v189
	v_mul_f32_e32 v206, 0x3f317217, v190
	v_mul_f32_e32 v207, 0x3f317217, v191
	v_fma_f32 v200, v184, s13, -v200
	v_fma_f32 v201, v185, s13, -v201
	v_fma_f32 v202, v186, s13, -v202
	v_fma_f32 v203, v187, s13, -v203
	v_fma_f32 v204, v188, s13, -v204
	v_fma_f32 v205, v189, s13, -v205
	v_fma_f32 v206, v190, s13, -v206
	v_fma_f32 v207, v191, s13, -v207
	v_fmac_f32_e32 v200, 0x3377d1cf, v184
	v_fmac_f32_e32 v201, 0x3377d1cf, v185
	v_fmac_f32_e32 v202, 0x3377d1cf, v186
	v_fmac_f32_e32 v203, 0x3377d1cf, v187
	v_fmac_f32_e32 v204, 0x3377d1cf, v188
	v_fmac_f32_e32 v205, 0x3377d1cf, v189
	v_fmac_f32_e32 v206, 0x3377d1cf, v190
	v_fmac_f32_e32 v207, 0x3377d1cf, v191
	v_fmac_f32_e32 v200, 0x3f317217, v184
	v_fmac_f32_e32 v201, 0x3f317217, v185
	v_fmac_f32_e32 v202, 0x3f317217, v186
	v_fmac_f32_e32 v203, 0x3f317217, v187
	v_fmac_f32_e32 v204, 0x3f317217, v188
	v_fmac_f32_e32 v205, 0x3f317217, v189
	v_fmac_f32_e32 v206, 0x3f317217, v190
	v_fmac_f32_e32 v207, 0x3f317217, v191
	v_cmp_lt_f32_e64 vcc, |v184|, s36
	v_cmp_lt_f32_e64 s[38:39], |v185|, s36
	v_cmp_lt_f32_e64 s[48:49], |v186|, s36
	v_cmp_lt_f32_e64 s[50:51], |v187|, s36
	v_cndmask_b32_e64 v184, v184, v200, vcc
	v_cndmask_b32_e64 v185, v185, v201, s[38:39]
	v_cndmask_b32_e64 v186, v186, v202, s[48:49]
	v_cndmask_b32_e64 v187, v187, v203, s[50:51]
	v_cmp_lt_f32_e64 vcc, |v188|, s36
	v_cmp_lt_f32_e64 s[38:39], |v189|, s36
	v_cmp_lt_f32_e64 s[48:49], |v190|, s36
	v_cmp_lt_f32_e64 s[50:51], |v191|, s36
	v_cndmask_b32_e64 v188, v188, v204, vcc
	v_cndmask_b32_e64 v189, v189, v205, s[38:39]
	v_cndmask_b32_e64 v190, v190, v206, s[48:49]
	v_cndmask_b32_e64 v191, v191, v207, s[50:51]
	v_sub_f32_e32 v60, v184, v192
	v_sub_f32_e32 v61, v185, v193
	v_sub_f32_e32 v62, v186, v194
	v_sub_f32_e32 v63, v187, v195
	v_sub_f32_e32 v56, v188, v196
	v_sub_f32_e32 v57, v189, v197
	v_sub_f32_e32 v58, v190, v198
	v_sub_f32_e32 v59, v191, v199
	v_cvt_pk_bf16_f32 v60, v60, v61
	v_cvt_pk_bf16_f32 v61, v62, v63
	v_cvt_pk_bf16_f32 v62, v56, v57
	v_cvt_pk_bf16_f32 v63, v58, v59
	global_store_dwordx4 v[162:163], v[60:63], off
	v_pk_mul_f32 v[52:53], v[52:53], v[148:149] op_sel_hi:[1,0]
	v_pk_mul_f32 v[54:55], v[54:55], v[148:149] op_sel_hi:[1,0]
	v_pk_mul_f32 v[48:49], v[48:49], v[148:149] op_sel_hi:[1,0]
	v_pk_mul_f32 v[50:51], v[50:51], v[148:149] op_sel_hi:[1,0]
	v_mul_f32_e32 v184, 0xbfb8aa3b, v52
; __device__ __forceinline__ unsigned cvt_pk_bf16(float lo, float hi) { unsigned r; asm volatile("v_cvt_pk_bf16_f32 %0, %1, %2" : "=v"(r) : "v"(lo), "v"(hi)); return r; }
; __device__ __forceinline__ float silu_f(float v) { return v * __builtin_amdgcn_rcpf(1.f + __expf(-v)); }
;     __device__ __forceinline__ void operator()(const f32x4 (&acc)[2][2][4][2], const Unit& u, int wr, int wc, int fr, int fq, int ui, PG8_LAS unsigned char* lds) const {
;     ...
;                     f32x4 v[2] = {acc[ai][bj][m][0] * rs, acc[ai][bj][m][1] * rs};
;                     if (ksum) { csum[bj][0] += v[0]; csum[bj][1] += v[1]; }
; #pragma unroll
;                     for (int n = 0; n < 2; ++n) {
;                         f32x4 lbv = (f32x4){0.f, 0.f, 0.f, 0.f};
;                         if (act == 2) lbv = *(const f32x4*)(lb + (col0 - 1024) + bj * HALF + 4 * n);
; #pragma unroll
;                         for (int e = 0; e < 4; ++e) {
;                             float x = v[n][e];
;                             if (act == 1) x = silu_f(x);
;                             else if (act == 2) { const float l = lbv[e]; x = __logf(l + (1.f - l) * __builtin_amdgcn_rcpf(1.f + __expf(-x))); }
;                             else if (act == 3) { x = fmaxf(x, 0.f); x = x * x; }
;                             v[n][e] = x;
;                         }
;                     }
;                     u32x4 w; w.x = cvt_pk_bf16(v[0][0], v[0][1]); w.y = cvt_pk_bf16(v[0][2], v[0][3]); w.z = cvt_pk_bf16(v[1][0], v[1][1]); w.w = cvt_pk_bf16(v[1][2], v[1][3]);
;                     *(u32x4*)(rowp + bj * HALF) = w;
	v_mul_f32_e32 v185, 0xbfb8aa3b, v53
	v_mul_f32_e32 v186, 0xbfb8aa3b, v54
	v_mul_f32_e32 v187, 0xbfb8aa3b, v55
	v_mul_f32_e32 v188, 0xbfb8aa3b, v48
	v_mul_f32_e32 v189, 0xbfb8aa3b, v49
	v_mul_f32_e32 v190, 0xbfb8aa3b, v50
	v_mul_f32_e32 v191, 0xbfb8aa3b, v51
	v_exp_f32_e32 v184, v184
	v_exp_f32_e32 v185, v185
	v_exp_f32_e32 v186, v186
	v_exp_f32_e32 v187, v187
	v_exp_f32_e32 v188, v188
	v_exp_f32_e32 v189, v189
	v_exp_f32_e32 v190, v190
	v_exp_f32_e32 v191, v191
	v_sub_f32_e32 v192, 1.0, v218
	v_sub_f32_e32 v193, 1.0, v219
	v_sub_f32_e32 v194, 1.0, v220
	v_sub_f32_e32 v195, 1.0, v221
	v_sub_f32_e32 v196, 1.0, v222
	v_sub_f32_e32 v197, 1.0, v223
	v_sub_f32_e32 v198, 1.0, v224
	v_sub_f32_e32 v199, 1.0, v225
	v_add_f32_e32 v184, 1.0, v184
	v_add_f32_e32 v185, 1.0, v185
	v_add_f32_e32 v186, 1.0, v186
	v_add_f32_e32 v187, 1.0, v187
	v_add_f32_e32 v188, 1.0, v188
	v_add_f32_e32 v189, 1.0, v189
	v_add_f32_e32 v190, 1.0, v190
	v_add_f32_e32 v191, 1.0, v191
	v_rcp_f32_e32 v184, v184
	v_rcp_f32_e32 v185, v185
	v_rcp_f32_e32 v186, v186
	v_rcp_f32_e32 v187, v187
	v_rcp_f32_e32 v188, v188
	v_rcp_f32_e32 v189, v189
	v_rcp_f32_e32 v190, v190
	v_rcp_f32_e32 v191, v191
	v_fma_f32 v200, v184, v192, v218
	v_fma_f32 v201, v185, v193, v219
	v_fma_f32 v202, v186, v194, v220
	v_fma_f32 v203, v187, v195, v221
	v_fma_f32 v204, v188, v196, v222
	v_fma_f32 v205, v189, v197, v223
	v_fma_f32 v206, v190, v198, v224
	v_fma_f32 v207, v191, v199, v225
	v_cmp_gt_f32_e64 vcc, s35, v200
	v_cmp_gt_f32_e64 s[38:39], s35, v201
	v_cmp_gt_f32_e64 s[48:49], s35, v202
	v_cmp_gt_f32_e64 s[50:51], s35, v203
	v_cndmask_b32_e64 v184, 0, 32, vcc
	v_cndmask_b32_e64 v185, 0, 32, s[38:39]
	v_cndmask_b32_e64 v186, 0, 32, s[48:49]
	v_cndmask_b32_e64 v187, 0, 32, s[50:51]
	v_cndmask_b32_e64 v192, 0, v214, vcc
	v_cndmask_b32_e64 v193, 0, v214, s[38:39]
	v_cndmask_b32_e64 v194, 0, v214, s[48:49]
	v_cndmask_b32_e64 v195, 0, v214, s[50:51]
	v_cmp_gt_f32_e64 vcc, s35, v204
	v_cmp_gt_f32_e64 s[38:39], s35, v205
	v_cmp_gt_f32_e64 s[48:49], s35, v206
	v_cmp_gt_f32_e64 s[50:51], s35, v207
	v_cndmask_b32_e64 v188, 0, 32, vcc
	v_cndmask_b32_e64 v189, 0, 32, s[38:39]
	v_cndmask_b32_e64 v190, 0, 32, s[48:49]
	v_cndmask_b32_e64 v191, 0, 32, s[50:51]
	v_cndmask_b32_e64 v196, 0, v214, vcc
	v_cndmask_b32_e64 v197, 0, v214, s[38:39]
	v_cndmask_b32_e64 v198, 0, v214, s[48:49]
	v_cndmask_b32_e64 v199, 0, v214, s[50:51]
	v_ldexp_f32 v184, v200, v184
	v_ldexp_f32 v185, v201, v185
	v_ldexp_f32 v186, v202, v186
	v_ldexp_f32 v187, v203, v187
	v_ldexp_f32 v188, v204, v188
	v_ldexp_f32 v189, v205, v189
	v_ldexp_f32 v190, v206, v190
	v_ldexp_f32 v191, v207, v191
	v_log_f32_e32 v184, v184
	v_log_f32_e32 v185, v185
	v_log_f32_e32 v186, v186
	v_log_f32_e32 v187, v187
	v_log_f32_e32 v188, v188
	v_log_f32_e32 v189, v189
	v_log_f32_e32 v190, v190
	v_log_f32_e32 v191, v191
	v_mul_f32_e32 v200, 0x3f317217, v184
	v_mul_f32_e32 v201, 0x3f317217, v185
	v_mul_f32_e32 v202, 0x3f317217, v186
	v_mul_f32_e32 v203, 0x3f317217, v187
	v_mul_f32_e32 v204, 0x3f317217, v188
	v_mul_f32_e32 v205, 0x3f317217, v189
	v_mul_f32_e32 v206, 0x3f317217, v190
	v_mul_f32_e32 v207, 0x3f317217, v191
	v_fma_f32 v200, v184, s13, -v200
	v_fma_f32 v201, v185, s13, -v201
	v_fma_f32 v202, v186, s13, -v202
	v_fma_f32 v203, v187, s13, -v203
	v_fma_f32 v204, v188, s13, -v204
	v_fma_f32 v205, v189, s13, -v205
	v_fma_f32 v206, v190, s13, -v206
	v_fma_f32 v207, v191, s13, -v207
	v_fmac_f32_e32 v200, 0x3377d1cf, v184
	v_fmac_f32_e32 v201, 0x3377d1cf, v185
	v_fmac_f32_e32 v202, 0x3377d1cf, v186
	v_fmac_f32_e32 v203, 0x3377d1cf, v187
	v_fmac_f32_e32 v204, 0x3377d1cf, v188
	v_fmac_f32_e32 v205, 0x3377d1cf, v189
	v_fmac_f32_e32 v206, 0x3377d1cf, v190
	v_fmac_f32_e32 v207, 0x3377d1cf, v191
	v_fmac_f32_e32 v200, 0x3f317217, v184
	v_fmac_f32_e32 v201, 0x3f317217, v185
	v_fmac_f32_e32 v202, 0x3f317217, v186
	v_fmac_f32_e32 v203, 0x3f317217, v187
	v_fmac_f32_e32 v204, 0x3f317217, v188
	v_fmac_f32_e32 v205, 0x3f317217, v189
	v_fmac_f32_e32 v206, 0x3f317217, v190
	v_fmac_f32_e32 v207, 0x3f317217, v191
	v_cmp_lt_f32_e64 vcc, |v184|, s36
	v_cmp_lt_f32_e64 s[38:39], |v185|, s36
	v_cmp_lt_f32_e64 s[48:49], |v186|, s36
	v_cmp_lt_f32_e64 s[50:51], |v187|, s36
	v_cndmask_b32_e64 v184, v184, v200, vcc
	v_cndmask_b32_e64 v185, v185, v201, s[38:39]
	v_cndmask_b32_e64 v186, v186, v202, s[48:49]
	v_cndmask_b32_e64 v187, v187, v203, s[50:51]
	v_cmp_lt_f32_e64 vcc, |v188|, s36
	v_cmp_lt_f32_e64 s[38:39], |v189|, s36
	v_cmp_lt_f32_e64 s[48:49], |v190|, s36
	v_cmp_lt_f32_e64 s[50:51], |v191|, s36
	v_cndmask_b32_e64 v188, v188, v204, vcc
	v_cndmask_b32_e64 v189, v189, v205, s[38:39]
	v_cndmask_b32_e64 v190, v190, v206, s[48:49]
	v_cndmask_b32_e64 v191, v191, v207, s[50:51]
	v_sub_f32_e32 v52, v184, v192
	v_sub_f32_e32 v53, v185, v193
	v_sub_f32_e32 v54, v186, v194
	v_sub_f32_e32 v55, v187, v195
	v_sub_f32_e32 v48, v188, v196
	v_sub_f32_e32 v49, v189, v197
	v_sub_f32_e32 v50, v190, v198
	v_sub_f32_e32 v51, v191, v199
	v_cvt_pk_bf16_f32 v52, v52, v53
	v_cvt_pk_bf16_f32 v53, v54, v55
	v_cvt_pk_bf16_f32 v54, v48, v49
	v_cvt_pk_bf16_f32 v55, v50, v51
	global_store_dwordx4 v[162:163], v[52:55], off offset:256
	v_lshl_add_u64 v[176:177], v[162:163], 0, s[46:47]
	v_pk_mul_f32 v[44:45], v[44:45], v[156:157] op_sel_hi:[1,0]
	v_pk_mul_f32 v[46:47], v[46:47], v[156:157] op_sel_hi:[1,0]
	v_pk_mul_f32 v[40:41], v[40:41], v[156:157] op_sel_hi:[1,0]
	v_pk_mul_f32 v[42:43], v[42:43], v[156:157] op_sel_hi:[1,0]
	v_mul_f32_e32 v184, 0xbfb8aa3b, v44
	v_mul_f32_e32 v185, 0xbfb8aa3b, v45
	v_mul_f32_e32 v186, 0xbfb8aa3b, v46
	v_mul_f32_e32 v187, 0xbfb8aa3b, v47
	v_mul_f32_e32 v188, 0xbfb8aa3b, v40
; __device__ __forceinline__ unsigned cvt_pk_bf16(float lo, float hi) { unsigned r; asm volatile("v_cvt_pk_bf16_f32 %0, %1, %2" : "=v"(r) : "v"(lo), "v"(hi)); return r; }
; __device__ __forceinline__ float silu_f(float v) { return v * __builtin_amdgcn_rcpf(1.f + __expf(-v)); }
;     __device__ __forceinline__ void operator()(const f32x4 (&acc)[2][2][4][2], const Unit& u, int wr, int wc, int fr, int fq, int ui, PG8_LAS unsigned char* lds) const {
;     ...
;                     f32x4 v[2] = {acc[ai][bj][m][0] * rs, acc[ai][bj][m][1] * rs};
;                     if (ksum) { csum[bj][0] += v[0]; csum[bj][1] += v[1]; }
; #pragma unroll
;                     for (int n = 0; n < 2; ++n) {
;                         f32x4 lbv = (f32x4){0.f, 0.f, 0.f, 0.f};
;                         if (act == 2) lbv = *(const f32x4*)(lb + (col0 - 1024) + bj * HALF + 4 * n);
; #pragma unroll
;                         for (int e = 0; e < 4; ++e) {
;                             float x = v[n][e];
;                             if (act == 1) x = silu_f(x);
;                             else if (act == 2) { const float l = lbv[e]; x = __logf(l + (1.f - l) * __builtin_amdgcn_rcpf(1.f + __expf(-x))); }
;                             else if (act == 3) { x = fmaxf(x, 0.f); x = x * x; }
;                             v[n][e] = x;
;                         }
;                     }
;                     u32x4 w; w.x = cvt_pk_bf16(v[0][0], v[0][1]); w.y = cvt_pk_bf16(v[0][2], v[0][3]); w.z = cvt_pk_bf16(v[1][0], v[1][1]); w.w = cvt_pk_bf16(v[1][2], v[1][3]);
;                     *(u32x4*)(rowp + bj * HALF) = w;
	v_mul_f32_e32 v189, 0xbfb8aa3b, v41
	v_mul_f32_e32 v190, 0xbfb8aa3b, v42
	v_mul_f32_e32 v191, 0xbfb8aa3b, v43
	v_exp_f32_e32 v184, v184
	v_exp_f32_e32 v185, v185
	v_exp_f32_e32 v186, v186
	v_exp_f32_e32 v187, v187
	v_exp_f32_e32 v188, v188
	v_exp_f32_e32 v189, v189
	v_exp_f32_e32 v190, v190
	v_exp_f32_e32 v191, v191
	v_sub_f32_e32 v192, 1.0, v152
	v_sub_f32_e32 v193, 1.0, v153
	v_sub_f32_e32 v194, 1.0, v154
	v_sub_f32_e32 v195, 1.0, v155
	v_sub_f32_e32 v196, 1.0, v180
	v_sub_f32_e32 v197, 1.0, v181
	v_sub_f32_e32 v198, 1.0, v182
	v_sub_f32_e32 v199, 1.0, v183
	v_add_f32_e32 v184, 1.0, v184
	v_add_f32_e32 v185, 1.0, v185
	v_add_f32_e32 v186, 1.0, v186
	v_add_f32_e32 v187, 1.0, v187
	v_add_f32_e32 v188, 1.0, v188
	v_add_f32_e32 v189, 1.0, v189
	v_add_f32_e32 v190, 1.0, v190
	v_add_f32_e32 v191, 1.0, v191
	v_rcp_f32_e32 v184, v184
	v_rcp_f32_e32 v185, v185
	v_rcp_f32_e32 v186, v186
	v_rcp_f32_e32 v187, v187
	v_rcp_f32_e32 v188, v188
	v_rcp_f32_e32 v189, v189
	v_rcp_f32_e32 v190, v190
	v_rcp_f32_e32 v191, v191
	v_fma_f32 v200, v184, v192, v152
	v_fma_f32 v201, v185, v193, v153
	v_fma_f32 v202, v186, v194, v154
	v_fma_f32 v203, v187, v195, v155
	v_fma_f32 v204, v188, v196, v180
	v_fma_f32 v205, v189, v197, v181
	v_fma_f32 v206, v190, v198, v182
	v_fma_f32 v207, v191, v199, v183
	v_cmp_gt_f32_e64 vcc, s35, v200
	v_cmp_gt_f32_e64 s[38:39], s35, v201
	v_cmp_gt_f32_e64 s[48:49], s35, v202
	v_cmp_gt_f32_e64 s[50:51], s35, v203
	v_cndmask_b32_e64 v184, 0, 32, vcc
	v_cndmask_b32_e64 v185, 0, 32, s[38:39]
	v_cndmask_b32_e64 v186, 0, 32, s[48:49]
	v_cndmask_b32_e64 v187, 0, 32, s[50:51]
	v_cndmask_b32_e64 v192, 0, v214, vcc
	v_cndmask_b32_e64 v193, 0, v214, s[38:39]
	v_cndmask_b32_e64 v194, 0, v214, s[48:49]
	v_cndmask_b32_e64 v195, 0, v214, s[50:51]
	v_cmp_gt_f32_e64 vcc, s35, v204
	v_cmp_gt_f32_e64 s[38:39], s35, v205
	v_cmp_gt_f32_e64 s[48:49], s35, v206
	v_cmp_gt_f32_e64 s[50:51], s35, v207
	v_cndmask_b32_e64 v188, 0, 32, vcc
	v_cndmask_b32_e64 v189, 0, 32, s[38:39]
	v_cndmask_b32_e64 v190, 0, 32, s[48:49]
	v_cndmask_b32_e64 v191, 0, 32, s[50:51]
	v_cndmask_b32_e64 v196, 0, v214, vcc
	v_cndmask_b32_e64 v197, 0, v214, s[38:39]
	v_cndmask_b32_e64 v198, 0, v214, s[48:49]
	v_cndmask_b32_e64 v199, 0, v214, s[50:51]
	v_ldexp_f32 v184, v200, v184
	v_ldexp_f32 v185, v201, v185
	v_ldexp_f32 v186, v202, v186
	v_ldexp_f32 v187, v203, v187
	v_ldexp_f32 v188, v204, v188
	v_ldexp_f32 v189, v205, v189
	v_ldexp_f32 v190, v206, v190
	v_ldexp_f32 v191, v207, v191
	v_log_f32_e32 v184, v184
	v_log_f32_e32 v185, v185
	v_log_f32_e32 v186, v186
	v_log_f32_e32 v187, v187
	v_log_f32_e32 v188, v188
	v_log_f32_e32 v189, v189
	v_log_f32_e32 v190, v190
	v_log_f32_e32 v191, v191
	v_mul_f32_e32 v200, 0x3f317217, v184
	v_mul_f32_e32 v201, 0x3f317217, v185
	v_mul_f32_e32 v202, 0x3f317217, v186
	v_mul_f32_e32 v203, 0x3f317217, v187
	v_mul_f32_e32 v204, 0x3f317217, v188
	v_mul_f32_e32 v205, 0x3f317217, v189
	v_mul_f32_e32 v206, 0x3f317217, v190
	v_mul_f32_e32 v207, 0x3f317217, v191
	v_fma_f32 v200, v184, s13, -v200
	v_fma_f32 v201, v185, s13, -v201
	v_fma_f32 v202, v186, s13, -v202
	v_fma_f32 v203, v187, s13, -v203
	v_fma_f32 v204, v188, s13, -v204
	v_fma_f32 v205, v189, s13, -v205
	v_fma_f32 v206, v190, s13, -v206
	v_fma_f32 v207, v191, s13, -v207
	v_fmac_f32_e32 v200, 0x3377d1cf, v184
	v_fmac_f32_e32 v201, 0x3377d1cf, v185
	v_fmac_f32_e32 v202, 0x3377d1cf, v186
	v_fmac_f32_e32 v203, 0x3377d1cf, v187
	v_fmac_f32_e32 v204, 0x3377d1cf, v188
	v_fmac_f32_e32 v205, 0x3377d1cf, v189
	v_fmac_f32_e32 v206, 0x3377d1cf, v190
	v_fmac_f32_e32 v207, 0x3377d1cf, v191
	v_fmac_f32_e32 v200, 0x3f317217, v184
	v_fmac_f32_e32 v201, 0x3f317217, v185
	v_fmac_f32_e32 v202, 0x3f317217, v186
	v_fmac_f32_e32 v203, 0x3f317217, v187
	v_fmac_f32_e32 v204, 0x3f317217, v188
	v_fmac_f32_e32 v205, 0x3f317217, v189
	v_fmac_f32_e32 v206, 0x3f317217, v190
	v_fmac_f32_e32 v207, 0x3f317217, v191
	v_cmp_lt_f32_e64 vcc, |v184|, s36
	v_cmp_lt_f32_e64 s[38:39], |v185|, s36
	v_cmp_lt_f32_e64 s[48:49], |v186|, s36
	v_cmp_lt_f32_e64 s[50:51], |v187|, s36
	v_cndmask_b32_e64 v184, v184, v200, vcc
	v_cndmask_b32_e64 v185, v185, v201, s[38:39]
	v_cndmask_b32_e64 v186, v186, v202, s[48:49]
	v_cndmask_b32_e64 v187, v187, v203, s[50:51]
	v_cmp_lt_f32_e64 vcc, |v188|, s36
	v_cmp_lt_f32_e64 s[38:39], |v189|, s36
	v_cmp_lt_f32_e64 s[48:49], |v190|, s36
	v_cmp_lt_f32_e64 s[50:51], |v191|, s36
	v_cndmask_b32_e64 v188, v188, v204, vcc
	v_cndmask_b32_e64 v189, v189, v205, s[38:39]
	v_cndmask_b32_e64 v190, v190, v206, s[48:49]
	v_cndmask_b32_e64 v191, v191, v207, s[50:51]
	v_sub_f32_e32 v44, v184, v192
	v_sub_f32_e32 v45, v185, v193
	v_sub_f32_e32 v46, v186, v194
	v_sub_f32_e32 v47, v187, v195
	v_sub_f32_e32 v40, v188, v196
	v_sub_f32_e32 v41, v189, v197
	v_sub_f32_e32 v42, v190, v198
	v_sub_f32_e32 v43, v191, v199
	v_cvt_pk_bf16_f32 v44, v44, v45
	v_cvt_pk_bf16_f32 v45, v46, v47
	v_cvt_pk_bf16_f32 v46, v40, v41
	v_cvt_pk_bf16_f32 v47, v42, v43
	global_store_dwordx4 v[176:177], v[44:47], off
	v_pk_mul_f32 v[36:37], v[36:37], v[156:157] op_sel_hi:[1,0]
	v_pk_mul_f32 v[38:39], v[38:39], v[156:157] op_sel_hi:[1,0]
	v_pk_mul_f32 v[32:33], v[32:33], v[156:157] op_sel_hi:[1,0]
	v_pk_mul_f32 v[34:35], v[34:35], v[156:157] op_sel_hi:[1,0]
	v_mul_f32_e32 v184, 0xbfb8aa3b, v36
	v_mul_f32_e32 v185, 0xbfb8aa3b, v37
	v_mul_f32_e32 v186, 0xbfb8aa3b, v38
	v_mul_f32_e32 v187, 0xbfb8aa3b, v39
	v_mul_f32_e32 v188, 0xbfb8aa3b, v32
	v_mul_f32_e32 v189, 0xbfb8aa3b, v33
	v_mul_f32_e32 v190, 0xbfb8aa3b, v34
	v_mul_f32_e32 v191, 0xbfb8aa3b, v35
	v_exp_f32_e32 v184, v184
	v_exp_f32_e32 v185, v185
	v_exp_f32_e32 v186, v186
	v_exp_f32_e32 v187, v187
; __device__ __forceinline__ unsigned cvt_pk_bf16(float lo, float hi) { unsigned r; asm volatile("v_cvt_pk_bf16_f32 %0, %1, %2" : "=v"(r) : "v"(lo), "v"(hi)); return r; }
; __device__ __forceinline__ float silu_f(float v) { return v * __builtin_amdgcn_rcpf(1.f + __expf(-v)); }
;     __device__ __forceinline__ void operator()(const f32x4 (&acc)[2][2][4][2], const Unit& u, int wr, int wc, int fr, int fq, int ui, PG8_LAS unsigned char* lds) const {
;     ...
;                     f32x4 v[2] = {acc[ai][bj][m][0] * rs, acc[ai][bj][m][1] * rs};
;                     if (ksum) { csum[bj][0] += v[0]; csum[bj][1] += v[1]; }
; #pragma unroll
;                     for (int n = 0; n < 2; ++n) {
;                         f32x4 lbv = (f32x4){0.f, 0.f, 0.f, 0.f};
;                         if (act == 2) lbv = *(const f32x4*)(lb + (col0 - 1024) + bj * HALF + 4 * n);
; #pragma unroll
;                         for (int e = 0; e < 4; ++e) {
;                             float x = v[n][e];
;                             if (act == 1) x = silu_f(x);
;                             else if (act == 2) { const float l = lbv[e]; x = __logf(l + (1.f - l) * __builtin_amdgcn_rcpf(1.f + __expf(-x))); }
;                             else if (act == 3) { x = fmaxf(x, 0.f); x = x * x; }
;                             v[n][e] = x;
;                         }
;                     }
;                     u32x4 w; w.x = cvt_pk_bf16(v[0][0], v[0][1]); w.y = cvt_pk_bf16(v[0][2], v[0][3]); w.z = cvt_pk_bf16(v[1][0], v[1][1]); w.w = cvt_pk_bf16(v[1][2], v[1][3]);
;                     *(u32x4*)(rowp + bj * HALF) = w;
	v_exp_f32_e32 v188, v188
	v_exp_f32_e32 v189, v189
	v_exp_f32_e32 v190, v190
	v_exp_f32_e32 v191, v191
	v_sub_f32_e32 v192, 1.0, v218
	v_sub_f32_e32 v193, 1.0, v219
	v_sub_f32_e32 v194, 1.0, v220
	v_sub_f32_e32 v195, 1.0, v221
	v_sub_f32_e32 v196, 1.0, v222
	v_sub_f32_e32 v197, 1.0, v223
	v_sub_f32_e32 v198, 1.0, v224
	v_sub_f32_e32 v199, 1.0, v225
	v_add_f32_e32 v184, 1.0, v184
	v_add_f32_e32 v185, 1.0, v185
	v_add_f32_e32 v186, 1.0, v186
	v_add_f32_e32 v187, 1.0, v187
	v_add_f32_e32 v188, 1.0, v188
	v_add_f32_e32 v189, 1.0, v189
	v_add_f32_e32 v190, 1.0, v190
	v_add_f32_e32 v191, 1.0, v191
	v_rcp_f32_e32 v184, v184
	v_rcp_f32_e32 v185, v185
	v_rcp_f32_e32 v186, v186
	v_rcp_f32_e32 v187, v187
	v_rcp_f32_e32 v188, v188
	v_rcp_f32_e32 v189, v189
	v_rcp_f32_e32 v190, v190
	v_rcp_f32_e32 v191, v191
	v_fma_f32 v200, v184, v192, v218
	v_fma_f32 v201, v185, v193, v219
	v_fma_f32 v202, v186, v194, v220
	v_fma_f32 v203, v187, v195, v221
	v_fma_f32 v204, v188, v196, v222
	v_fma_f32 v205, v189, v197, v223
	v_fma_f32 v206, v190, v198, v224
	v_fma_f32 v207, v191, v199, v225
	v_cmp_gt_f32_e64 vcc, s35, v200
	v_cmp_gt_f32_e64 s[38:39], s35, v201
	v_cmp_gt_f32_e64 s[48:49], s35, v202
	v_cmp_gt_f32_e64 s[50:51], s35, v203
	v_cndmask_b32_e64 v184, 0, 32, vcc
	v_cndmask_b32_e64 v185, 0, 32, s[38:39]
	v_cndmask_b32_e64 v186, 0, 32, s[48:49]
	v_cndmask_b32_e64 v187, 0, 32, s[50:51]
	v_cndmask_b32_e64 v192, 0, v214, vcc
	v_cndmask_b32_e64 v193, 0, v214, s[38:39]
	v_cndmask_b32_e64 v194, 0, v214, s[48:49]
	v_cndmask_b32_e64 v195, 0, v214, s[50:51]
	v_cmp_gt_f32_e64 vcc, s35, v204
	v_cmp_gt_f32_e64 s[38:39], s35, v205
	v_cmp_gt_f32_e64 s[48:49], s35, v206
	v_cmp_gt_f32_e64 s[50:51], s35, v207
	v_cndmask_b32_e64 v188, 0, 32, vcc
	v_cndmask_b32_e64 v189, 0, 32, s[38:39]
	v_cndmask_b32_e64 v190, 0, 32, s[48:49]
	v_cndmask_b32_e64 v191, 0, 32, s[50:51]
	v_cndmask_b32_e64 v196, 0, v214, vcc
	v_cndmask_b32_e64 v197, 0, v214, s[38:39]
	v_cndmask_b32_e64 v198, 0, v214, s[48:49]
	v_cndmask_b32_e64 v199, 0, v214, s[50:51]
	v_ldexp_f32 v184, v200, v184
	v_ldexp_f32 v185, v201, v185
	v_ldexp_f32 v186, v202, v186
	v_ldexp_f32 v187, v203, v187
	v_ldexp_f32 v188, v204, v188
	v_ldexp_f32 v189, v205, v189
	v_ldexp_f32 v190, v206, v190
	v_ldexp_f32 v191, v207, v191
	v_log_f32_e32 v184, v184
	v_log_f32_e32 v185, v185
	v_log_f32_e32 v186, v186
	v_log_f32_e32 v187, v187
	v_log_f32_e32 v188, v188
	v_log_f32_e32 v189, v189
	v_log_f32_e32 v190, v190
	v_log_f32_e32 v191, v191
	v_mul_f32_e32 v200, 0x3f317217, v184
	v_mul_f32_e32 v201, 0x3f317217, v185
	v_mul_f32_e32 v202, 0x3f317217, v186
	v_mul_f32_e32 v203, 0x3f317217, v187
	v_mul_f32_e32 v204, 0x3f317217, v188
	v_mul_f32_e32 v205, 0x3f317217, v189
	v_mul_f32_e32 v206, 0x3f317217, v190
	v_mul_f32_e32 v207, 0x3f317217, v191
	v_fma_f32 v200, v184, s13, -v200
	v_fma_f32 v201, v185, s13, -v201
	v_fma_f32 v202, v186, s13, -v202
	v_fma_f32 v203, v187, s13, -v203
	v_fma_f32 v204, v188, s13, -v204
	v_fma_f32 v205, v189, s13, -v205
	v_fma_f32 v206, v190, s13, -v206
	v_fma_f32 v207, v191, s13, -v207
	v_fmac_f32_e32 v200, 0x3377d1cf, v184
	v_fmac_f32_e32 v201, 0x3377d1cf, v185
	v_fmac_f32_e32 v202, 0x3377d1cf, v186
	v_fmac_f32_e32 v203, 0x3377d1cf, v187
	v_fmac_f32_e32 v204, 0x3377d1cf, v188
	v_fmac_f32_e32 v205, 0x3377d1cf, v189
	v_fmac_f32_e32 v206, 0x3377d1cf, v190
	v_fmac_f32_e32 v207, 0x3377d1cf, v191
	v_fmac_f32_e32 v200, 0x3f317217, v184
	v_fmac_f32_e32 v201, 0x3f317217, v185
	v_fmac_f32_e32 v202, 0x3f317217, v186
	v_fmac_f32_e32 v203, 0x3f317217, v187
	v_fmac_f32_e32 v204, 0x3f317217, v188
	v_fmac_f32_e32 v205, 0x3f317217, v189
	v_fmac_f32_e32 v206, 0x3f317217, v190
	v_fmac_f32_e32 v207, 0x3f317217, v191
	v_cmp_lt_f32_e64 vcc, |v184|, s36
	v_cmp_lt_f32_e64 s[38:39], |v185|, s36
	v_cmp_lt_f32_e64 s[48:49], |v186|, s36
	v_cmp_lt_f32_e64 s[50:51], |v187|, s36
	v_cndmask_b32_e64 v184, v184, v200, vcc
	v_cndmask_b32_e64 v185, v185, v201, s[38:39]
	v_cndmask_b32_e64 v186, v186, v202, s[48:49]
	v_cndmask_b32_e64 v187, v187, v203, s[50:51]
	v_cmp_lt_f32_e64 vcc, |v188|, s36
	v_cmp_lt_f32_e64 s[38:39], |v189|, s36
	v_cmp_lt_f32_e64 s[48:49], |v190|, s36
	v_cmp_lt_f32_e64 s[50:51], |v191|, s36
	v_cndmask_b32_e64 v188, v188, v204, vcc
	v_cndmask_b32_e64 v189, v189, v205, s[38:39]
	v_cndmask_b32_e64 v190, v190, v206, s[48:49]
	v_cndmask_b32_e64 v191, v191, v207, s[50:51]
	v_sub_f32_e32 v36, v184, v192
	v_sub_f32_e32 v37, v185, v193
	v_sub_f32_e32 v38, v186, v194
	v_sub_f32_e32 v39, v187, v195
	v_sub_f32_e32 v32, v188, v196
	v_sub_f32_e32 v33, v189, v197
	v_sub_f32_e32 v34, v190, v198
	v_sub_f32_e32 v35, v191, v199
	v_cvt_pk_bf16_f32 v36, v36, v37
	v_cvt_pk_bf16_f32 v37, v38, v39
	v_cvt_pk_bf16_f32 v38, v32, v33
	v_cvt_pk_bf16_f32 v39, v34, v35
	global_store_dwordx4 v[176:177], v[36:39], off offset:256
	v_lshl_add_u64 v[162:163], v[176:177], 0, s[46:47]
	v_pk_mul_f32 v[28:29], v[28:29], v[158:159] op_sel_hi:[1,0]
	v_pk_mul_f32 v[30:31], v[30:31], v[158:159] op_sel_hi:[1,0]
	v_pk_mul_f32 v[24:25], v[24:25], v[158:159] op_sel_hi:[1,0]
	v_pk_mul_f32 v[26:27], v[26:27], v[158:159] op_sel_hi:[1,0]
	v_mul_f32_e32 v184, 0xbfb8aa3b, v28
	v_mul_f32_e32 v185, 0xbfb8aa3b, v29
	v_mul_f32_e32 v186, 0xbfb8aa3b, v30
	v_mul_f32_e32 v187, 0xbfb8aa3b, v31
	v_mul_f32_e32 v188, 0xbfb8aa3b, v24
	v_mul_f32_e32 v189, 0xbfb8aa3b, v25
	v_mul_f32_e32 v190, 0xbfb8aa3b, v26
	v_mul_f32_e32 v191, 0xbfb8aa3b, v27
	v_exp_f32_e32 v184, v184
	v_exp_f32_e32 v185, v185
	v_exp_f32_e32 v186, v186
	v_exp_f32_e32 v187, v187
	v_exp_f32_e32 v188, v188
	v_exp_f32_e32 v189, v189
	v_exp_f32_e32 v190, v190
	v_exp_f32_e32 v191, v191
	v_sub_f32_e32 v192, 1.0, v152
	v_sub_f32_e32 v193, 1.0, v153
; __device__ __forceinline__ unsigned cvt_pk_bf16(float lo, float hi) { unsigned r; asm volatile("v_cvt_pk_bf16_f32 %0, %1, %2" : "=v"(r) : "v"(lo), "v"(hi)); return r; }
; __device__ __forceinline__ float silu_f(float v) { return v * __builtin_amdgcn_rcpf(1.f + __expf(-v)); }
;     __device__ __forceinline__ void operator()(const f32x4 (&acc)[2][2][4][2], const Unit& u, int wr, int wc, int fr, int fq, int ui, PG8_LAS unsigned char* lds) const {
;     ...
;                     f32x4 v[2] = {acc[ai][bj][m][0] * rs, acc[ai][bj][m][1] * rs};
;                     if (ksum) { csum[bj][0] += v[0]; csum[bj][1] += v[1]; }
; #pragma unroll
;                     for (int n = 0; n < 2; ++n) {
;                         f32x4 lbv = (f32x4){0.f, 0.f, 0.f, 0.f};
;                         if (act == 2) lbv = *(const f32x4*)(lb + (col0 - 1024) + bj * HALF + 4 * n);
; #pragma unroll
;                         for (int e = 0; e < 4; ++e) {
;                             float x = v[n][e];
;                             if (act == 1) x = silu_f(x);
;                             else if (act == 2) { const float l = lbv[e]; x = __logf(l + (1.f - l) * __builtin_amdgcn_rcpf(1.f + __expf(-x))); }
;                             else if (act == 3) { x = fmaxf(x, 0.f); x = x * x; }
;                             v[n][e] = x;
;                         }
;                     }
;                     u32x4 w; w.x = cvt_pk_bf16(v[0][0], v[0][1]); w.y = cvt_pk_bf16(v[0][2], v[0][3]); w.z = cvt_pk_bf16(v[1][0], v[1][1]); w.w = cvt_pk_bf16(v[1][2], v[1][3]);
;                     *(u32x4*)(rowp + bj * HALF) = w;
	v_sub_f32_e32 v194, 1.0, v154
	v_sub_f32_e32 v195, 1.0, v155
	v_sub_f32_e32 v196, 1.0, v180
	v_sub_f32_e32 v197, 1.0, v181
	v_sub_f32_e32 v198, 1.0, v182
	v_sub_f32_e32 v199, 1.0, v183
	v_add_f32_e32 v184, 1.0, v184
	v_add_f32_e32 v185, 1.0, v185
	v_add_f32_e32 v186, 1.0, v186
	v_add_f32_e32 v187, 1.0, v187
	v_add_f32_e32 v188, 1.0, v188
	v_add_f32_e32 v189, 1.0, v189
	v_add_f32_e32 v190, 1.0, v190
	v_add_f32_e32 v191, 1.0, v191
	v_rcp_f32_e32 v184, v184
	v_rcp_f32_e32 v185, v185
	v_rcp_f32_e32 v186, v186
	v_rcp_f32_e32 v187, v187
	v_rcp_f32_e32 v188, v188
	v_rcp_f32_e32 v189, v189
	v_rcp_f32_e32 v190, v190
	v_rcp_f32_e32 v191, v191
	v_fma_f32 v200, v184, v192, v152
	v_fma_f32 v201, v185, v193, v153
	v_fma_f32 v202, v186, v194, v154
	v_fma_f32 v203, v187, v195, v155
	v_fma_f32 v204, v188, v196, v180
	v_fma_f32 v205, v189, v197, v181
	v_fma_f32 v206, v190, v198, v182
	v_fma_f32 v207, v191, v199, v183
	v_cmp_gt_f32_e64 vcc, s35, v200
	v_cmp_gt_f32_e64 s[38:39], s35, v201
	v_cmp_gt_f32_e64 s[48:49], s35, v202
	v_cmp_gt_f32_e64 s[50:51], s35, v203
	v_cndmask_b32_e64 v184, 0, 32, vcc
	v_cndmask_b32_e64 v185, 0, 32, s[38:39]
	v_cndmask_b32_e64 v186, 0, 32, s[48:49]
	v_cndmask_b32_e64 v187, 0, 32, s[50:51]
	v_cndmask_b32_e64 v192, 0, v214, vcc
	v_cndmask_b32_e64 v193, 0, v214, s[38:39]
	v_cndmask_b32_e64 v194, 0, v214, s[48:49]
	v_cndmask_b32_e64 v195, 0, v214, s[50:51]
	v_cmp_gt_f32_e64 vcc, s35, v204
	v_cmp_gt_f32_e64 s[38:39], s35, v205
	v_cmp_gt_f32_e64 s[48:49], s35, v206
	v_cmp_gt_f32_e64 s[50:51], s35, v207
	v_cndmask_b32_e64 v188, 0, 32, vcc
	v_cndmask_b32_e64 v189, 0, 32, s[38:39]
	v_cndmask_b32_e64 v190, 0, 32, s[48:49]
	v_cndmask_b32_e64 v191, 0, 32, s[50:51]
	v_cndmask_b32_e64 v196, 0, v214, vcc
	v_cndmask_b32_e64 v197, 0, v214, s[38:39]
	v_cndmask_b32_e64 v198, 0, v214, s[48:49]
	v_cndmask_b32_e64 v199, 0, v214, s[50:51]
	v_ldexp_f32 v184, v200, v184
	v_ldexp_f32 v185, v201, v185
	v_ldexp_f32 v186, v202, v186
	v_ldexp_f32 v187, v203, v187
	v_ldexp_f32 v188, v204, v188
	v_ldexp_f32 v189, v205, v189
	v_ldexp_f32 v190, v206, v190
	v_ldexp_f32 v191, v207, v191
	v_log_f32_e32 v184, v184
	v_log_f32_e32 v185, v185
	v_log_f32_e32 v186, v186
	v_log_f32_e32 v187, v187
	v_log_f32_e32 v188, v188
	v_log_f32_e32 v189, v189
	v_log_f32_e32 v190, v190
	v_log_f32_e32 v191, v191
	v_mul_f32_e32 v200, 0x3f317217, v184
	v_mul_f32_e32 v201, 0x3f317217, v185
	v_mul_f32_e32 v202, 0x3f317217, v186
	v_mul_f32_e32 v203, 0x3f317217, v187
	v_mul_f32_e32 v204, 0x3f317217, v188
	v_mul_f32_e32 v205, 0x3f317217, v189
	v_mul_f32_e32 v206, 0x3f317217, v190
	v_mul_f32_e32 v207, 0x3f317217, v191
	v_fma_f32 v200, v184, s13, -v200
	v_fma_f32 v201, v185, s13, -v201
	v_fma_f32 v202, v186, s13, -v202
	v_fma_f32 v203, v187, s13, -v203
	v_fma_f32 v204, v188, s13, -v204
	v_fma_f32 v205, v189, s13, -v205
	v_fma_f32 v206, v190, s13, -v206
	v_fma_f32 v207, v191, s13, -v207
	v_fmac_f32_e32 v200, 0x3377d1cf, v184
	v_fmac_f32_e32 v201, 0x3377d1cf, v185
	v_fmac_f32_e32 v202, 0x3377d1cf, v186
	v_fmac_f32_e32 v203, 0x3377d1cf, v187
	v_fmac_f32_e32 v204, 0x3377d1cf, v188
	v_fmac_f32_e32 v205, 0x3377d1cf, v189
	v_fmac_f32_e32 v206, 0x3377d1cf, v190
	v_fmac_f32_e32 v207, 0x3377d1cf, v191
	v_fmac_f32_e32 v200, 0x3f317217, v184
	v_fmac_f32_e32 v201, 0x3f317217, v185
	v_fmac_f32_e32 v202, 0x3f317217, v186
	v_fmac_f32_e32 v203, 0x3f317217, v187
	v_fmac_f32_e32 v204, 0x3f317217, v188
	v_fmac_f32_e32 v205, 0x3f317217, v189
	v_fmac_f32_e32 v206, 0x3f317217, v190
	v_fmac_f32_e32 v207, 0x3f317217, v191
	v_cmp_lt_f32_e64 vcc, |v184|, s36
	v_cmp_lt_f32_e64 s[38:39], |v185|, s36
	v_cmp_lt_f32_e64 s[48:49], |v186|, s36
	v_cmp_lt_f32_e64 s[50:51], |v187|, s36
	v_cndmask_b32_e64 v184, v184, v200, vcc
	v_cndmask_b32_e64 v185, v185, v201, s[38:39]
	v_cndmask_b32_e64 v186, v186, v202, s[48:49]
	v_cndmask_b32_e64 v187, v187, v203, s[50:51]
	v_cmp_lt_f32_e64 vcc, |v188|, s36
	v_cmp_lt_f32_e64 s[38:39], |v189|, s36
	v_cmp_lt_f32_e64 s[48:49], |v190|, s36
	v_cmp_lt_f32_e64 s[50:51], |v191|, s36
	v_cndmask_b32_e64 v188, v188, v204, vcc
	v_cndmask_b32_e64 v189, v189, v205, s[38:39]
	v_cndmask_b32_e64 v190, v190, v206, s[48:49]
	v_cndmask_b32_e64 v191, v191, v207, s[50:51]
	v_sub_f32_e32 v28, v184, v192
	v_sub_f32_e32 v29, v185, v193
	v_sub_f32_e32 v30, v186, v194
	v_sub_f32_e32 v31, v187, v195
	v_sub_f32_e32 v24, v188, v196
	v_sub_f32_e32 v25, v189, v197
	v_sub_f32_e32 v26, v190, v198
	v_sub_f32_e32 v27, v191, v199
	v_cvt_pk_bf16_f32 v28, v28, v29
	v_cvt_pk_bf16_f32 v29, v30, v31
	v_cvt_pk_bf16_f32 v30, v24, v25
	v_cvt_pk_bf16_f32 v31, v26, v27
	global_store_dwordx4 v[162:163], v[28:31], off
	v_pk_mul_f32 v[20:21], v[20:21], v[158:159] op_sel_hi:[1,0]
	v_pk_mul_f32 v[22:23], v[22:23], v[158:159] op_sel_hi:[1,0]
	v_pk_mul_f32 v[16:17], v[16:17], v[158:159] op_sel_hi:[1,0]
	v_pk_mul_f32 v[18:19], v[18:19], v[158:159] op_sel_hi:[1,0]
	v_mul_f32_e32 v184, 0xbfb8aa3b, v20
	v_mul_f32_e32 v185, 0xbfb8aa3b, v21
	v_mul_f32_e32 v186, 0xbfb8aa3b, v22
	v_mul_f32_e32 v187, 0xbfb8aa3b, v23
	v_mul_f32_e32 v188, 0xbfb8aa3b, v16
	v_mul_f32_e32 v189, 0xbfb8aa3b, v17
	v_mul_f32_e32 v190, 0xbfb8aa3b, v18
	v_mul_f32_e32 v191, 0xbfb8aa3b, v19
	v_exp_f32_e32 v184, v184
	v_exp_f32_e32 v185, v185
	v_exp_f32_e32 v186, v186
	v_exp_f32_e32 v187, v187
	v_exp_f32_e32 v188, v188
	v_exp_f32_e32 v189, v189
	v_exp_f32_e32 v190, v190
	v_exp_f32_e32 v191, v191
	v_sub_f32_e32 v192, 1.0, v218
	v_sub_f32_e32 v193, 1.0, v219
	v_sub_f32_e32 v194, 1.0, v220
	v_sub_f32_e32 v195, 1.0, v221
	v_sub_f32_e32 v196, 1.0, v222
	v_sub_f32_e32 v197, 1.0, v223
	v_sub_f32_e32 v198, 1.0, v224
	v_sub_f32_e32 v199, 1.0, v225
	v_add_f32_e32 v184, 1.0, v184
; __device__ __forceinline__ unsigned cvt_pk_bf16(float lo, float hi) { unsigned r; asm volatile("v_cvt_pk_bf16_f32 %0, %1, %2" : "=v"(r) : "v"(lo), "v"(hi)); return r; }
; __device__ __forceinline__ float silu_f(float v) { return v * __builtin_amdgcn_rcpf(1.f + __expf(-v)); }
;     __device__ __forceinline__ void operator()(const f32x4 (&acc)[2][2][4][2], const Unit& u, int wr, int wc, int fr, int fq, int ui, PG8_LAS unsigned char* lds) const {
;     ...
;                     f32x4 v[2] = {acc[ai][bj][m][0] * rs, acc[ai][bj][m][1] * rs};
;                     if (ksum) { csum[bj][0] += v[0]; csum[bj][1] += v[1]; }
; #pragma unroll
;                     for (int n = 0; n < 2; ++n) {
;                         f32x4 lbv = (f32x4){0.f, 0.f, 0.f, 0.f};
;                         if (act == 2) lbv = *(const f32x4*)(lb + (col0 - 1024) + bj * HALF + 4 * n);
; #pragma unroll
;                         for (int e = 0; e < 4; ++e) {
;                             float x = v[n][e];
;                             if (act == 1) x = silu_f(x);
;                             else if (act == 2) { const float l = lbv[e]; x = __logf(l + (1.f - l) * __builtin_amdgcn_rcpf(1.f + __expf(-x))); }
;                             else if (act == 3) { x = fmaxf(x, 0.f); x = x * x; }
;                             v[n][e] = x;
;                         }
;                     }
;                     u32x4 w; w.x = cvt_pk_bf16(v[0][0], v[0][1]); w.y = cvt_pk_bf16(v[0][2], v[0][3]); w.z = cvt_pk_bf16(v[1][0], v[1][1]); w.w = cvt_pk_bf16(v[1][2], v[1][3]);
;                     *(u32x4*)(rowp + bj * HALF) = w;
	v_add_f32_e32 v185, 1.0, v185
	v_add_f32_e32 v186, 1.0, v186
	v_add_f32_e32 v187, 1.0, v187
	v_add_f32_e32 v188, 1.0, v188
	v_add_f32_e32 v189, 1.0, v189
	v_add_f32_e32 v190, 1.0, v190
	v_add_f32_e32 v191, 1.0, v191
	v_rcp_f32_e32 v184, v184
	v_rcp_f32_e32 v185, v185
	v_rcp_f32_e32 v186, v186
	v_rcp_f32_e32 v187, v187
	v_rcp_f32_e32 v188, v188
	v_rcp_f32_e32 v189, v189
	v_rcp_f32_e32 v190, v190
	v_rcp_f32_e32 v191, v191
	v_fma_f32 v200, v184, v192, v218
	v_fma_f32 v201, v185, v193, v219
	v_fma_f32 v202, v186, v194, v220
	v_fma_f32 v203, v187, v195, v221
	v_fma_f32 v204, v188, v196, v222
	v_fma_f32 v205, v189, v197, v223
	v_fma_f32 v206, v190, v198, v224
	v_fma_f32 v207, v191, v199, v225
	v_cmp_gt_f32_e64 vcc, s35, v200
	v_cmp_gt_f32_e64 s[38:39], s35, v201
	v_cmp_gt_f32_e64 s[48:49], s35, v202
	v_cmp_gt_f32_e64 s[50:51], s35, v203
	v_cndmask_b32_e64 v184, 0, 32, vcc
	v_cndmask_b32_e64 v185, 0, 32, s[38:39]
	v_cndmask_b32_e64 v186, 0, 32, s[48:49]
	v_cndmask_b32_e64 v187, 0, 32, s[50:51]
	v_cndmask_b32_e64 v192, 0, v214, vcc
	v_cndmask_b32_e64 v193, 0, v214, s[38:39]
	v_cndmask_b32_e64 v194, 0, v214, s[48:49]
	v_cndmask_b32_e64 v195, 0, v214, s[50:51]
	v_cmp_gt_f32_e64 vcc, s35, v204
	v_cmp_gt_f32_e64 s[38:39], s35, v205
	v_cmp_gt_f32_e64 s[48:49], s35, v206
	v_cmp_gt_f32_e64 s[50:51], s35, v207
	v_cndmask_b32_e64 v188, 0, 32, vcc
	v_cndmask_b32_e64 v189, 0, 32, s[38:39]
	v_cndmask_b32_e64 v190, 0, 32, s[48:49]
	v_cndmask_b32_e64 v191, 0, 32, s[50:51]
	v_cndmask_b32_e64 v196, 0, v214, vcc
	v_cndmask_b32_e64 v197, 0, v214, s[38:39]
	v_cndmask_b32_e64 v198, 0, v214, s[48:49]
	v_cndmask_b32_e64 v199, 0, v214, s[50:51]
	v_ldexp_f32 v184, v200, v184
	v_ldexp_f32 v185, v201, v185
	v_ldexp_f32 v186, v202, v186
	v_ldexp_f32 v187, v203, v187
	v_ldexp_f32 v188, v204, v188
	v_ldexp_f32 v189, v205, v189
	v_ldexp_f32 v190, v206, v190
	v_ldexp_f32 v191, v207, v191
	v_log_f32_e32 v184, v184
	v_log_f32_e32 v185, v185
	v_log_f32_e32 v186, v186
	v_log_f32_e32 v187, v187
	v_log_f32_e32 v188, v188
	v_log_f32_e32 v189, v189
	v_log_f32_e32 v190, v190
	v_log_f32_e32 v191, v191
	v_mul_f32_e32 v200, 0x3f317217, v184
	v_mul_f32_e32 v201, 0x3f317217, v185
	v_mul_f32_e32 v202, 0x3f317217, v186
	v_mul_f32_e32 v203, 0x3f317217, v187
	v_mul_f32_e32 v204, 0x3f317217, v188
	v_mul_f32_e32 v205, 0x3f317217, v189
	v_mul_f32_e32 v206, 0x3f317217, v190
	v_mul_f32_e32 v207, 0x3f317217, v191
	v_fma_f32 v200, v184, s13, -v200
	v_fma_f32 v201, v185, s13, -v201
	v_fma_f32 v202, v186, s13, -v202
	v_fma_f32 v203, v187, s13, -v203
	v_fma_f32 v204, v188, s13, -v204
	v_fma_f32 v205, v189, s13, -v205
	v_fma_f32 v206, v190, s13, -v206
	v_fma_f32 v207, v191, s13, -v207
	v_fmac_f32_e32 v200, 0x3377d1cf, v184
	v_fmac_f32_e32 v201, 0x3377d1cf, v185
	v_fmac_f32_e32 v202, 0x3377d1cf, v186
	v_fmac_f32_e32 v203, 0x3377d1cf, v187
	v_fmac_f32_e32 v204, 0x3377d1cf, v188
	v_fmac_f32_e32 v205, 0x3377d1cf, v189
	v_fmac_f32_e32 v206, 0x3377d1cf, v190
	v_fmac_f32_e32 v207, 0x3377d1cf, v191
	v_fmac_f32_e32 v200, 0x3f317217, v184
	v_fmac_f32_e32 v201, 0x3f317217, v185
	v_fmac_f32_e32 v202, 0x3f317217, v186
	v_fmac_f32_e32 v203, 0x3f317217, v187
	v_fmac_f32_e32 v204, 0x3f317217, v188
	v_fmac_f32_e32 v205, 0x3f317217, v189
	v_fmac_f32_e32 v206, 0x3f317217, v190
	v_fmac_f32_e32 v207, 0x3f317217, v191
	v_cmp_lt_f32_e64 vcc, |v184|, s36
	v_cmp_lt_f32_e64 s[38:39], |v185|, s36
	v_cmp_lt_f32_e64 s[48:49], |v186|, s36
	v_cmp_lt_f32_e64 s[50:51], |v187|, s36
	v_cndmask_b32_e64 v184, v184, v200, vcc
	v_cndmask_b32_e64 v185, v185, v201, s[38:39]
	v_cndmask_b32_e64 v186, v186, v202, s[48:49]
	v_cndmask_b32_e64 v187, v187, v203, s[50:51]
	v_cmp_lt_f32_e64 vcc, |v188|, s36
	v_cmp_lt_f32_e64 s[38:39], |v189|, s36
	v_cmp_lt_f32_e64 s[48:49], |v190|, s36
	v_cmp_lt_f32_e64 s[50:51], |v191|, s36
	v_cndmask_b32_e64 v188, v188, v204, vcc
	v_cndmask_b32_e64 v189, v189, v205, s[38:39]
	v_cndmask_b32_e64 v190, v190, v206, s[48:49]
	v_cndmask_b32_e64 v191, v191, v207, s[50:51]
	v_sub_f32_e32 v20, v184, v192
	v_sub_f32_e32 v21, v185, v193
	v_sub_f32_e32 v22, v186, v194
	v_sub_f32_e32 v23, v187, v195
	v_sub_f32_e32 v16, v188, v196
	v_sub_f32_e32 v17, v189, v197
	v_sub_f32_e32 v18, v190, v198
	v_sub_f32_e32 v19, v191, v199
	v_cvt_pk_bf16_f32 v20, v20, v21
	v_cvt_pk_bf16_f32 v21, v22, v23
	v_cvt_pk_bf16_f32 v22, v16, v17
	v_cvt_pk_bf16_f32 v23, v18, v19
	global_store_dwordx4 v[162:163], v[20:23], off offset:256
	v_lshl_add_u64 v[176:177], v[162:163], 0, s[46:47]
	v_pk_mul_f32 v[12:13], v[12:13], v[160:161] op_sel_hi:[1,0]
	v_pk_mul_f32 v[14:15], v[14:15], v[160:161] op_sel_hi:[1,0]
	v_pk_mul_f32 v[8:9], v[8:9], v[160:161] op_sel_hi:[1,0]
	v_pk_mul_f32 v[10:11], v[10:11], v[160:161] op_sel_hi:[1,0]
	v_mul_f32_e32 v184, 0xbfb8aa3b, v12
	v_mul_f32_e32 v185, 0xbfb8aa3b, v13
	v_mul_f32_e32 v186, 0xbfb8aa3b, v14
	v_mul_f32_e32 v187, 0xbfb8aa3b, v15
	v_mul_f32_e32 v188, 0xbfb8aa3b, v8
	v_mul_f32_e32 v189, 0xbfb8aa3b, v9
	v_mul_f32_e32 v190, 0xbfb8aa3b, v10
	v_mul_f32_e32 v191, 0xbfb8aa3b, v11
	v_exp_f32_e32 v184, v184
	v_exp_f32_e32 v185, v185
	v_exp_f32_e32 v186, v186
	v_exp_f32_e32 v187, v187
	v_exp_f32_e32 v188, v188
	v_exp_f32_e32 v189, v189
	v_exp_f32_e32 v190, v190
	v_exp_f32_e32 v191, v191
	v_sub_f32_e32 v192, 1.0, v152
	v_sub_f32_e32 v193, 1.0, v153
	v_sub_f32_e32 v194, 1.0, v154
	v_sub_f32_e32 v195, 1.0, v155
	v_sub_f32_e32 v196, 1.0, v180
	v_sub_f32_e32 v197, 1.0, v181
	v_sub_f32_e32 v198, 1.0, v182
	v_sub_f32_e32 v199, 1.0, v183
	v_add_f32_e32 v184, 1.0, v184
	v_add_f32_e32 v185, 1.0, v185
	v_add_f32_e32 v186, 1.0, v186
	v_add_f32_e32 v187, 1.0, v187
	v_add_f32_e32 v188, 1.0, v188
	v_add_f32_e32 v189, 1.0, v189
; __device__ __forceinline__ unsigned cvt_pk_bf16(float lo, float hi) { unsigned r; asm volatile("v_cvt_pk_bf16_f32 %0, %1, %2" : "=v"(r) : "v"(lo), "v"(hi)); return r; }
; __device__ __forceinline__ float silu_f(float v) { return v * __builtin_amdgcn_rcpf(1.f + __expf(-v)); }
;     __device__ __forceinline__ void operator()(const f32x4 (&acc)[2][2][4][2], const Unit& u, int wr, int wc, int fr, int fq, int ui, PG8_LAS unsigned char* lds) const {
;     ...
;                     f32x4 v[2] = {acc[ai][bj][m][0] * rs, acc[ai][bj][m][1] * rs};
;                     if (ksum) { csum[bj][0] += v[0]; csum[bj][1] += v[1]; }
; #pragma unroll
;                     for (int n = 0; n < 2; ++n) {
;                         f32x4 lbv = (f32x4){0.f, 0.f, 0.f, 0.f};
;                         if (act == 2) lbv = *(const f32x4*)(lb + (col0 - 1024) + bj * HALF + 4 * n);
; #pragma unroll
;                         for (int e = 0; e < 4; ++e) {
;                             float x = v[n][e];
;                             if (act == 1) x = silu_f(x);
;                             else if (act == 2) { const float l = lbv[e]; x = __logf(l + (1.f - l) * __builtin_amdgcn_rcpf(1.f + __expf(-x))); }
;                             else if (act == 3) { x = fmaxf(x, 0.f); x = x * x; }
;                             v[n][e] = x;
;                         }
;                     }
;                     u32x4 w; w.x = cvt_pk_bf16(v[0][0], v[0][1]); w.y = cvt_pk_bf16(v[0][2], v[0][3]); w.z = cvt_pk_bf16(v[1][0], v[1][1]); w.w = cvt_pk_bf16(v[1][2], v[1][3]);
;                     *(u32x4*)(rowp + bj * HALF) = w;
	v_add_f32_e32 v190, 1.0, v190
	v_add_f32_e32 v191, 1.0, v191
	v_rcp_f32_e32 v184, v184
	v_rcp_f32_e32 v185, v185
	v_rcp_f32_e32 v186, v186
	v_rcp_f32_e32 v187, v187
	v_rcp_f32_e32 v188, v188
	v_rcp_f32_e32 v189, v189
	v_rcp_f32_e32 v190, v190
	v_rcp_f32_e32 v191, v191
	v_fma_f32 v200, v184, v192, v152
	v_fma_f32 v201, v185, v193, v153
	v_fma_f32 v202, v186, v194, v154
	v_fma_f32 v203, v187, v195, v155
	v_fma_f32 v204, v188, v196, v180
	v_fma_f32 v205, v189, v197, v181
	v_fma_f32 v206, v190, v198, v182
	v_fma_f32 v207, v191, v199, v183
	v_cmp_gt_f32_e64 vcc, s35, v200
	v_cmp_gt_f32_e64 s[38:39], s35, v201
	v_cmp_gt_f32_e64 s[48:49], s35, v202
	v_cmp_gt_f32_e64 s[50:51], s35, v203
	v_cndmask_b32_e64 v184, 0, 32, vcc
	v_cndmask_b32_e64 v185, 0, 32, s[38:39]
	v_cndmask_b32_e64 v186, 0, 32, s[48:49]
	v_cndmask_b32_e64 v187, 0, 32, s[50:51]
	v_cndmask_b32_e64 v192, 0, v214, vcc
	v_cndmask_b32_e64 v193, 0, v214, s[38:39]
	v_cndmask_b32_e64 v194, 0, v214, s[48:49]
	v_cndmask_b32_e64 v195, 0, v214, s[50:51]
	v_cmp_gt_f32_e64 vcc, s35, v204
	v_cmp_gt_f32_e64 s[38:39], s35, v205
	v_cmp_gt_f32_e64 s[48:49], s35, v206
	v_cmp_gt_f32_e64 s[50:51], s35, v207
	v_cndmask_b32_e64 v188, 0, 32, vcc
	v_cndmask_b32_e64 v189, 0, 32, s[38:39]
	v_cndmask_b32_e64 v190, 0, 32, s[48:49]
	v_cndmask_b32_e64 v191, 0, 32, s[50:51]
	v_cndmask_b32_e64 v196, 0, v214, vcc
	v_cndmask_b32_e64 v197, 0, v214, s[38:39]
	v_cndmask_b32_e64 v198, 0, v214, s[48:49]
	v_cndmask_b32_e64 v199, 0, v214, s[50:51]
	v_ldexp_f32 v184, v200, v184
	v_ldexp_f32 v185, v201, v185
	v_ldexp_f32 v186, v202, v186
	v_ldexp_f32 v187, v203, v187
	v_ldexp_f32 v188, v204, v188
	v_ldexp_f32 v189, v205, v189
	v_ldexp_f32 v190, v206, v190
	v_ldexp_f32 v191, v207, v191
	v_log_f32_e32 v184, v184
	v_log_f32_e32 v185, v185
	v_log_f32_e32 v186, v186
	v_log_f32_e32 v187, v187
	v_log_f32_e32 v188, v188
	v_log_f32_e32 v189, v189
	v_log_f32_e32 v190, v190
	v_log_f32_e32 v191, v191
	v_mul_f32_e32 v200, 0x3f317217, v184
	v_mul_f32_e32 v201, 0x3f317217, v185
	v_mul_f32_e32 v202, 0x3f317217, v186
	v_mul_f32_e32 v203, 0x3f317217, v187
	v_mul_f32_e32 v204, 0x3f317217, v188
	v_mul_f32_e32 v205, 0x3f317217, v189
	v_mul_f32_e32 v206, 0x3f317217, v190
	v_mul_f32_e32 v207, 0x3f317217, v191
	v_fma_f32 v200, v184, s13, -v200
	v_fma_f32 v201, v185, s13, -v201
	v_fma_f32 v202, v186, s13, -v202
	v_fma_f32 v203, v187, s13, -v203
	v_fma_f32 v204, v188, s13, -v204
	v_fma_f32 v205, v189, s13, -v205
	v_fma_f32 v206, v190, s13, -v206
	v_fma_f32 v207, v191, s13, -v207
	v_fmac_f32_e32 v200, 0x3377d1cf, v184
	v_fmac_f32_e32 v201, 0x3377d1cf, v185
	v_fmac_f32_e32 v202, 0x3377d1cf, v186
	v_fmac_f32_e32 v203, 0x3377d1cf, v187
	v_fmac_f32_e32 v204, 0x3377d1cf, v188
	v_fmac_f32_e32 v205, 0x3377d1cf, v189
	v_fmac_f32_e32 v206, 0x3377d1cf, v190
	v_fmac_f32_e32 v207, 0x3377d1cf, v191
	v_fmac_f32_e32 v200, 0x3f317217, v184
	v_fmac_f32_e32 v201, 0x3f317217, v185
	v_fmac_f32_e32 v202, 0x3f317217, v186
	v_fmac_f32_e32 v203, 0x3f317217, v187
	v_fmac_f32_e32 v204, 0x3f317217, v188
	v_fmac_f32_e32 v205, 0x3f317217, v189
	v_fmac_f32_e32 v206, 0x3f317217, v190
	v_fmac_f32_e32 v207, 0x3f317217, v191
	v_cmp_lt_f32_e64 vcc, |v184|, s36
	v_cmp_lt_f32_e64 s[38:39], |v185|, s36
	v_cmp_lt_f32_e64 s[48:49], |v186|, s36
	v_cmp_lt_f32_e64 s[50:51], |v187|, s36
	v_cndmask_b32_e64 v184, v184, v200, vcc
	v_cndmask_b32_e64 v185, v185, v201, s[38:39]
	v_cndmask_b32_e64 v186, v186, v202, s[48:49]
	v_cndmask_b32_e64 v187, v187, v203, s[50:51]
	v_cmp_lt_f32_e64 vcc, |v188|, s36
	v_cmp_lt_f32_e64 s[38:39], |v189|, s36
	v_cmp_lt_f32_e64 s[48:49], |v190|, s36
	v_cmp_lt_f32_e64 s[50:51], |v191|, s36
	v_cndmask_b32_e64 v188, v188, v204, vcc
	v_cndmask_b32_e64 v189, v189, v205, s[38:39]
	v_cndmask_b32_e64 v190, v190, v206, s[48:49]
	v_cndmask_b32_e64 v191, v191, v207, s[50:51]
	v_sub_f32_e32 v12, v184, v192
	v_sub_f32_e32 v13, v185, v193
	v_sub_f32_e32 v14, v186, v194
	v_sub_f32_e32 v15, v187, v195
	v_sub_f32_e32 v8, v188, v196
	v_sub_f32_e32 v9, v189, v197
	v_sub_f32_e32 v10, v190, v198
	v_sub_f32_e32 v11, v191, v199
	v_cvt_pk_bf16_f32 v12, v12, v13
	v_cvt_pk_bf16_f32 v13, v14, v15
	v_cvt_pk_bf16_f32 v14, v8, v9
	v_cvt_pk_bf16_f32 v15, v10, v11
	global_store_dwordx4 v[176:177], v[12:15], off
	v_pk_mul_f32 v[4:5], v[4:5], v[160:161] op_sel_hi:[1,0]
	v_pk_mul_f32 v[6:7], v[6:7], v[160:161] op_sel_hi:[1,0]
	v_pk_mul_f32 v[0:1], v[0:1], v[160:161] op_sel_hi:[1,0]
	v_pk_mul_f32 v[2:3], v[2:3], v[160:161] op_sel_hi:[1,0]
	v_mul_f32_e32 v184, 0xbfb8aa3b, v4
	v_mul_f32_e32 v185, 0xbfb8aa3b, v5
	v_mul_f32_e32 v186, 0xbfb8aa3b, v6
	v_mul_f32_e32 v187, 0xbfb8aa3b, v7
	v_mul_f32_e32 v188, 0xbfb8aa3b, v0
	v_mul_f32_e32 v189, 0xbfb8aa3b, v1
	v_mul_f32_e32 v190, 0xbfb8aa3b, v2
	v_mul_f32_e32 v191, 0xbfb8aa3b, v3
	v_exp_f32_e32 v184, v184
	v_exp_f32_e32 v185, v185
	v_exp_f32_e32 v186, v186
; __device__ __forceinline__ unsigned cvt_pk_bf16(float lo, float hi) { unsigned r; asm volatile("v_cvt_pk_bf16_f32 %0, %1, %2" : "=v"(r) : "v"(lo), "v"(hi)); return r; }
; __device__ __forceinline__ float silu_f(float v) { return v * __builtin_amdgcn_rcpf(1.f + __expf(-v)); }
;     __device__ __forceinline__ void operator()(const f32x4 (&acc)[2][2][4][2], const Unit& u, int wr, int wc, int fr, int fq, int ui, PG8_LAS unsigned char* lds) const {
;     ...
;                     f32x4 v[2] = {acc[ai][bj][m][0] * rs, acc[ai][bj][m][1] * rs};
;                     if (ksum) { csum[bj][0] += v[0]; csum[bj][1] += v[1]; }
; #pragma unroll
;                     for (int n = 0; n < 2; ++n) {
;                         f32x4 lbv = (f32x4){0.f, 0.f, 0.f, 0.f};
;                         if (act == 2) lbv = *(const f32x4*)(lb + (col0 - 1024) + bj * HALF + 4 * n);
; #pragma unroll
;                         for (int e = 0; e < 4; ++e) {
;                             float x = v[n][e];
;                             if (act == 1) x = silu_f(x);
;                             else if (act == 2) { const float l = lbv[e]; x = __logf(l + (1.f - l) * __builtin_amdgcn_rcpf(1.f + __expf(-x))); }
;                             else if (act == 3) { x = fmaxf(x, 0.f); x = x * x; }
;                             v[n][e] = x;
;                         }
;                     }
;                     u32x4 w; w.x = cvt_pk_bf16(v[0][0], v[0][1]); w.y = cvt_pk_bf16(v[0][2], v[0][3]); w.z = cvt_pk_bf16(v[1][0], v[1][1]); w.w = cvt_pk_bf16(v[1][2], v[1][3]);
;                     *(u32x4*)(rowp + bj * HALF) = w;
	v_exp_f32_e32 v187, v187
	v_exp_f32_e32 v188, v188
	v_exp_f32_e32 v189, v189
	v_exp_f32_e32 v190, v190
	v_exp_f32_e32 v191, v191
	v_sub_f32_e32 v192, 1.0, v218
	v_sub_f32_e32 v193, 1.0, v219
	v_sub_f32_e32 v194, 1.0, v220
	v_sub_f32_e32 v195, 1.0, v221
	v_sub_f32_e32 v196, 1.0, v222
	v_sub_f32_e32 v197, 1.0, v223
	v_sub_f32_e32 v198, 1.0, v224
	v_sub_f32_e32 v199, 1.0, v225
	v_add_f32_e32 v184, 1.0, v184
	v_add_f32_e32 v185, 1.0, v185
	v_add_f32_e32 v186, 1.0, v186
	v_add_f32_e32 v187, 1.0, v187
	v_add_f32_e32 v188, 1.0, v188
	v_add_f32_e32 v189, 1.0, v189
	v_add_f32_e32 v190, 1.0, v190
	v_add_f32_e32 v191, 1.0, v191
	v_rcp_f32_e32 v184, v184
	v_rcp_f32_e32 v185, v185
	v_rcp_f32_e32 v186, v186
	v_rcp_f32_e32 v187, v187
	v_rcp_f32_e32 v188, v188
	v_rcp_f32_e32 v189, v189
	v_rcp_f32_e32 v190, v190
	v_rcp_f32_e32 v191, v191
	v_fma_f32 v200, v184, v192, v218
	v_fma_f32 v201, v185, v193, v219
	v_fma_f32 v202, v186, v194, v220
	v_fma_f32 v203, v187, v195, v221
	v_fma_f32 v204, v188, v196, v222
	v_fma_f32 v205, v189, v197, v223
	v_fma_f32 v206, v190, v198, v224
	v_fma_f32 v207, v191, v199, v225
	v_cmp_gt_f32_e64 vcc, s35, v200
	v_cmp_gt_f32_e64 s[38:39], s35, v201
	v_cmp_gt_f32_e64 s[48:49], s35, v202
	v_cmp_gt_f32_e64 s[50:51], s35, v203
	v_cndmask_b32_e64 v184, 0, 32, vcc
	v_cndmask_b32_e64 v185, 0, 32, s[38:39]
	v_cndmask_b32_e64 v186, 0, 32, s[48:49]
	v_cndmask_b32_e64 v187, 0, 32, s[50:51]
	v_cndmask_b32_e64 v192, 0, v214, vcc
	v_cndmask_b32_e64 v193, 0, v214, s[38:39]
	v_cndmask_b32_e64 v194, 0, v214, s[48:49]
	v_cndmask_b32_e64 v195, 0, v214, s[50:51]
	v_cmp_gt_f32_e64 vcc, s35, v204
	v_cmp_gt_f32_e64 s[38:39], s35, v205
	v_cmp_gt_f32_e64 s[48:49], s35, v206
	v_cmp_gt_f32_e64 s[50:51], s35, v207
	v_cndmask_b32_e64 v188, 0, 32, vcc
	v_cndmask_b32_e64 v189, 0, 32, s[38:39]
	v_cndmask_b32_e64 v190, 0, 32, s[48:49]
	v_cndmask_b32_e64 v191, 0, 32, s[50:51]
	v_cndmask_b32_e64 v196, 0, v214, vcc
	v_cndmask_b32_e64 v197, 0, v214, s[38:39]
	v_cndmask_b32_e64 v198, 0, v214, s[48:49]
	v_cndmask_b32_e64 v199, 0, v214, s[50:51]
	v_ldexp_f32 v184, v200, v184
	v_ldexp_f32 v185, v201, v185
	v_ldexp_f32 v186, v202, v186
	v_ldexp_f32 v187, v203, v187
	v_ldexp_f32 v188, v204, v188
	v_ldexp_f32 v189, v205, v189
	v_ldexp_f32 v190, v206, v190
	v_ldexp_f32 v191, v207, v191
	v_log_f32_e32 v184, v184
	v_log_f32_e32 v185, v185
	v_log_f32_e32 v186, v186
	v_log_f32_e32 v187, v187
	v_log_f32_e32 v188, v188
	v_log_f32_e32 v189, v189
	v_log_f32_e32 v190, v190
	v_log_f32_e32 v191, v191
	v_mul_f32_e32 v200, 0x3f317217, v184
	v_mul_f32_e32 v201, 0x3f317217, v185
	v_mul_f32_e32 v202, 0x3f317217, v186
	v_mul_f32_e32 v203, 0x3f317217, v187
	v_mul_f32_e32 v204, 0x3f317217, v188
	v_mul_f32_e32 v205, 0x3f317217, v189
	v_mul_f32_e32 v206, 0x3f317217, v190
	v_mul_f32_e32 v207, 0x3f317217, v191
	v_fma_f32 v200, v184, s13, -v200
	v_fma_f32 v201, v185, s13, -v201
	v_fma_f32 v202, v186, s13, -v202
	v_fma_f32 v203, v187, s13, -v203
	v_fma_f32 v204, v188, s13, -v204
	v_fma_f32 v205, v189, s13, -v205
	v_fma_f32 v206, v190, s13, -v206
	v_fma_f32 v207, v191, s13, -v207
	v_fmac_f32_e32 v200, 0x3377d1cf, v184
	v_fmac_f32_e32 v201, 0x3377d1cf, v185
	v_fmac_f32_e32 v202, 0x3377d1cf, v186
	v_fmac_f32_e32 v203, 0x3377d1cf, v187
	v_fmac_f32_e32 v204, 0x3377d1cf, v188
	v_fmac_f32_e32 v205, 0x3377d1cf, v189
	v_fmac_f32_e32 v206, 0x3377d1cf, v190
	v_fmac_f32_e32 v207, 0x3377d1cf, v191
	v_fmac_f32_e32 v200, 0x3f317217, v184
	v_fmac_f32_e32 v201, 0x3f317217, v185
	v_fmac_f32_e32 v202, 0x3f317217, v186
	v_fmac_f32_e32 v203, 0x3f317217, v187
	v_fmac_f32_e32 v204, 0x3f317217, v188
	v_fmac_f32_e32 v205, 0x3f317217, v189
	v_fmac_f32_e32 v206, 0x3f317217, v190
	v_fmac_f32_e32 v207, 0x3f317217, v191
	v_cmp_lt_f32_e64 vcc, |v184|, s36
	v_cmp_lt_f32_e64 s[38:39], |v185|, s36
	v_cmp_lt_f32_e64 s[48:49], |v186|, s36
	v_cmp_lt_f32_e64 s[50:51], |v187|, s36
	v_cndmask_b32_e64 v184, v184, v200, vcc
	v_cndmask_b32_e64 v185, v185, v201, s[38:39]
	v_cndmask_b32_e64 v186, v186, v202, s[48:49]
	v_cndmask_b32_e64 v187, v187, v203, s[50:51]
	v_cmp_lt_f32_e64 vcc, |v188|, s36
	v_cmp_lt_f32_e64 s[38:39], |v189|, s36
	v_cmp_lt_f32_e64 s[48:49], |v190|, s36
	v_cmp_lt_f32_e64 s[50:51], |v191|, s36
	v_cndmask_b32_e64 v188, v188, v204, vcc
	v_cndmask_b32_e64 v189, v189, v205, s[38:39]
	v_cndmask_b32_e64 v190, v190, v206, s[48:49]
	v_cndmask_b32_e64 v191, v191, v207, s[50:51]
	v_sub_f32_e32 v4, v184, v192
	v_sub_f32_e32 v5, v185, v193
	v_sub_f32_e32 v6, v186, v194
	v_sub_f32_e32 v7, v187, v195
	v_sub_f32_e32 v0, v188, v196
	v_sub_f32_e32 v1, v189, v197
	v_sub_f32_e32 v2, v190, v198
	v_sub_f32_e32 v3, v191, v199
	v_cvt_pk_bf16_f32 v4, v4, v5
	v_cvt_pk_bf16_f32 v5, v6, v7
	v_cvt_pk_bf16_f32 v6, v0, v1
	v_cvt_pk_bf16_f32 v7, v2, v3
	global_store_dwordx4 v[176:177], v[4:7], off offset:256
	s_branch .LBB0_1108
